# indexer key matrix KI stored tile-swizzled by the in-proj epilogue so each indexer B-fragment load is one contiguous 1KiB per wave instruction (was 64 scattered 16B pieces)
# speedup vs baseline: 1.0593x; 1.0553x over previous
; #define PG8_WAIT_V(n) asm volatile("s_waitcnt vmcnt(" #n ")" ::: "memory")
; template <class Epi, class Sched, bool ALIGN_EPI = false, bool SP2 = false>
; __device__ __forceinline__ void gemm_phase(PG8_LAS unsigned char* lds, const Gemm g, const Sched& S, const Epi& E, const int wid_in) {
;     ...
;         PG8_WAIT_V(2); PG8_BAR;
;         PG8_STAGE(PG8_SB(1, 0), cB + kstep, voffB); PG8_STAGE(PG8_SA(1, 0), cA + kstep, voffA); PG8_STAGE(PG8_SB(1, 1), cB + hstep + kstep, voffB);
;         PG8_WAIT_V(6); PG8_BAR;
;     __device__ __forceinline__ void operator()(const f32x4 (&acc)[2][2][4][2], const pg8::Unit& u, int wr, int wc, int fr, int fq) const {
;         GAS f16* const Q = (GAS f16*)(wsb + WS_Q); GAS f16* const K = (GAS f16*)(wsb + WS_K); GAS f16* const V = (GAS f16*)(wsb + WS_V); GAS f16* const QI = (GAS f16*)(wsb + WS_QI); GAS f16* const KI = (GAS f16*)(wsb + WS_KI);
;         GAS f16* const GLU = (GAS f16*)(wsb + WS_GLU); GAS f16* const GA = (GAS f16*)(wsb + WS_GA); GAS f16* const GC = (GAS f16*)(wsb + WS_GC); GAS float* const WI = (GAS float*)(wsb + WS_WI);
;         const int row0 = u.pm * 256 + wr * 64 + fr;
;         const int pn = u.pn;
;         if (pn < 4) {
;             const bool isq = pn < 2; const LAS float* g = gtab + (isq ? 0 : 64); GAS f16* O = isq ? Q : K;
;             const int head = 4 * (pn & 1) + wc; const float sc = isq ? 0.125f * 1.4426950408889634f : 1.f;
;             f32x4 gv[2][2];
; #pragma unroll
;             for (int bj = 0; bj < 2; ++bj)
; #pragma unroll
;                 for (int n = 0; n < 2; ++n) gv[bj][n] = *(const LAS f32x4*)(g + 32 * bj + 8 * fq + 4 * n);
; #pragma unroll
;             for (int ai = 0; ai < 2; ++ai)
; #pragma unroll
;                 for (int m = 0; m < 4; ++m) {
;                     float ss = (sq4(acc[ai][0][m][0]) + sq4(acc[ai][0][m][1])) + (sq4(acc[ai][1][m][0]) + sq4(acc[ai][1][m][1]));
;                     ss += __shfl_xor(ss, 16); ss += __shfl_xor(ss, 32);
;                     const float rinv = __builtin_amdgcn_rsqf(ss * (1.f / 64.f) + EPS) * sc;
;                     GAS f16* rowp = O + (size_t)(row0 + ai * 128 + m * 16) * 512 + head * 64 + 8 * fq;
; #pragma unroll
;                     for (int bj = 0; bj < 2; ++bj) *(GAS u32x4*)(rowp + 32 * bj) = pack8_bf16(acc[ai][bj][m][0] * rinv * gv[bj][0], acc[ai][bj][m][1] * rinv * gv[bj][1]);
;                 }
;         } else if (pn < 8) {
.LBB0_139:
	s_mov_b64 s[16:17], 0x80
	s_add_i32 m0, s63, 0x18000
	v_lshl_add_u64 v[8:9], v[8:9], 0, s[16:17]
	s_waitcnt vmcnt(2)
	s_barrier
	global_load_lds_dwordx4 v[8:9], off
	v_lshl_add_u64 v[4:5], v[4:5], 0, s[16:17]
	s_add_i32 m0, s63, 0x1a000
	s_add_i32 s69, s63, 0x8000
	global_load_lds_dwordx4 v[4:5], off
	v_lshl_add_u64 v[4:5], v[6:7], 0, s[16:17]
	s_mov_b32 m0, s69
	s_add_i32 s70, s63, 0xa000
	global_load_lds_dwordx4 v[4:5], off
	v_lshl_add_u64 v[4:5], v[10:11], 0, s[16:17]
	s_mov_b32 m0, s70
	v_lshl_add_u64 v[2:3], v[2:3], 0, s[16:17]
	global_load_lds_dwordx4 v[4:5], off
	s_add_i32 m0, s63, 0x1c000
	v_lshl_add_u64 v[0:1], v[0:1], 0, s[16:17]
	global_load_lds_dwordx4 v[2:3], off
	s_add_i32 m0, s63, 0x1e000
	s_lshr_b32 s5, s7, 26
	global_load_lds_dwordx4 v[0:1], off
	s_add_i32 s5, s6, s5
	s_ashr_i32 s68, s5, 6
	s_cmp_gt_i32 s6, 63
	s_cselect_b64 s[18:19], -1, 0
	s_add_i32 s71, s68, -2
	s_cmpk_lt_u32 s93, 0x100
	s_cselect_b64 s[20:21], -1, 0
	s_add_u32 s22, s28, 0x8c00000
	v_and_b32_e32 v21, 15, v12
	v_readlane_b32 s5, v248, 3
	s_addc_u32 s23, s29, 0
	s_add_u32 s24, s28, 0x8a00000
	v_or_b32_e32 v170, s5, v21
	v_lshlrev_b32_e32 v22, 6, v170
	v_and_b32_e32 v23, 48, v12
	s_movk_i32 s5, 0x3c0
	s_addc_u32 s25, s29, 0
	v_and_or_b32 v22, v22, s5, v23
	v_and_b32_e32 v19, 0xfffffc00, v19
	v_readlane_b32 s5, v248, 4
	s_cmp_gt_u32 s80, 1
	v_ashrrev_i32_e32 v20, 4, v12
	v_add_u32_e32 v24, s5, v19
	v_readlane_b32 s5, v248, 6
	s_cselect_b64 s[26:27], -1, 0
	s_cmp_eq_u32 s80, 2
	v_lshlrev_b32_e32 v152, 3, v20
	v_add_u32_e32 v1, s5, v19
	v_readlane_b32 s5, v248, 5
	s_cselect_b64 s[6:7], -1, 0
	v_cmp_gt_u32_e32 vcc, 16, v12
	v_lshlrev_b32_e32 v0, 2, v170
	v_add_u32_e32 v172, s5, v152
	s_and_b64 s[38:39], s[6:7], vcc
	s_lshl_b32 s5, s5, 4
	v_and_b32_e32 v0, 32, v0
	v_lshlrev_b32_e32 v3, 2, v12
	s_add_u32 s6, s28, s5
	v_bitop3_b32 v2, v22, v24, v0 bitop3:0xde
	v_lshl_or_b32 v0, v21, 6, v23
	v_and_b32_e32 v3, 32, v3
	s_addc_u32 s7, s29, 0
	v_ashrrev_i32_e32 v153, 31, v152
	v_bitop3_b32 v171, v0, v1, v3 bitop3:0xde
	v_lshlrev_b64 v[0:1], 7, v[152:153]
	v_lshl_add_u64 v[0:1], v[0:1], 0, s[6:7]
	s_mov_b64 s[6:7], 0x8800000
	v_lshl_add_u64 v[154:155], v[0:1], 0, s[6:7]
	v_add_u32_e32 v0, v15, v13
	v_add_lshl_u32 v0, v0, v14, 1
	v_mov_b32_e32 v1, v147
	s_waitcnt vmcnt(6)
	v_lshl_add_u64 v[156:157], s[10:11], 0, v[0:1]
	v_add_u32_e32 v0, v18, v16
	s_add_i32 s5, 0, 0x20000
	v_add_lshl_u32 v0, v0, v17, 1
	s_add_i32 s78, 0, 0x10000
	s_add_i32 s81, 0, 0x14000
	v_add_u32_e32 v173, 0xfffffb80, v172
	s_mov_b32 s72, 0x20000
	v_lshl_add_u32 v174, v20, 5, s5
	s_ashr_i32 s73, s30, 31
	s_mov_b32 s76, s30
	s_ashr_i32 s77, s2, 31
	v_lshl_add_u64 v[158:159], s[10:11], 0, v[0:1]
	v_mov_b64_e32 v[160:161], 0x540
	v_mov_b64_e32 v[162:163], 0x53f
	v_add_u32_e32 v175, s78, v171
	v_add_u32_e32 v176, s81, v171
	v_add_u32_e32 v177, 0, v2
	s_mov_b32 s82, 0x50000
	s_mov_b64 s[40:41], 0x58000
	s_mov_b32 s83, 0x58000
	s_mov_b32 s85, 0x24000
	s_mov_b32 s86, 0x28000
	s_mov_b32 s87, 0x2c000
	s_mov_b32 s42, 0x3eb504f3
	s_mov_b32 s44, 0x3e000000
	s_mov_b32 s88, 0x6800000
	s_mov_b64 s[46:47], 0x20000
	s_mov_b64 s[48:49], 0x24000
	s_mov_b64 s[50:51], 0x28000
	s_mov_b64 s[52:53], 0x2c000
	s_mov_b32 s89, 0x4800000
	v_mov_b32_e32 v178, 0x358637bd
	v_mov_b32_e32 v179, 0x3e38aa3b
	v_mbcnt_hi_u32_b32 v180, -1, v195
	s_barrier
	s_branch .LBB0_142

; #define GAS __attribute__((address_space(1)))
;     __device__ __forceinline__ void operator()(const f32x4 (&acc)[2][2][4][2], const pg8::Unit& u, int wr, int wc, int fr, int fq) const {
;     ...
;                 for (int m = 0; m < 4; ++m) { const size_t row = (size_t)(row0 + ai * 128 + m * 16);
;                     if (wc < 2) *(GAS h8*)(KI + row * 64 + 32 * wc + 8 * fq) = pack8(acc[ai][0][m][0], acc[ai][0][m][1]);
.LBB0_168:
	s_andn2_b64 vcc, exec, s[8:9]
	s_cbranch_vccnz .LBB0_170
	v_and_b32_e32 v134, 31, v164
	v_mul_u32_u24_e32 v134, 0x70, v134
	v_lshlrev_b64 v[132:133], 7, v[164:165]
	v_sub_u32_e32 v132, v132, v134
	v_cvt_pk_f16_f32 v131, v122, v123
	v_cvt_pk_f16_f32 v130, v120, v121
	v_cvt_pk_f16_f32 v129, v126, v127
	v_cvt_pk_f16_f32 v128, v124, v125
	v_lshl_add_u64 v[132:133], v[154:155], 0, v[132:133]
	global_store_dwordx4 v[132:133], v[128:131], off

; #define GAS __attribute__((address_space(1)))
;     __device__ __forceinline__ void operator()(const f32x4 (&acc)[2][2][4][2], const pg8::Unit& u, int wr, int wc, int fr, int fq) const {
;     ...
;                 for (int m = 0; m < 4; ++m) { const size_t row = (size_t)(row0 + ai * 128 + m * 16);
;                     if (wc < 2) *(GAS h8*)(KI + row * 64 + 32 * wc + 8 * fq) = pack8(acc[ai][0][m][0], acc[ai][0][m][1]);
.LBB0_174:
	s_andn2_b64 vcc, exec, s[58:59]
	s_cbranch_vccnz .LBB0_176
	v_and_b32_e32 v134, 31, v128
	v_mul_u32_u24_e32 v134, 0x70, v134
	v_lshlrev_b64 v[128:129], 7, v[128:129]
	v_sub_u32_e32 v128, v128, v134
	v_cvt_pk_f16_f32 v133, v106, v107
	v_cvt_pk_f16_f32 v132, v104, v105
	v_cvt_pk_f16_f32 v131, v110, v111
	v_cvt_pk_f16_f32 v130, v108, v109
	v_lshl_add_u64 v[128:129], v[154:155], 0, v[128:129]
	global_store_dwordx4 v[128:129], v[130:133], off

; #define GAS __attribute__((address_space(1)))
;     __device__ __forceinline__ void operator()(const f32x4 (&acc)[2][2][4][2], const pg8::Unit& u, int wr, int wc, int fr, int fq) const {
;     ...
;                 for (int m = 0; m < 4; ++m) { const size_t row = (size_t)(row0 + ai * 128 + m * 16);
;                     if (wc < 2) *(GAS h8*)(KI + row * 64 + 32 * wc + 8 * fq) = pack8(acc[ai][0][m][0], acc[ai][0][m][1]);
.LBB0_180:
	s_andn2_b64 vcc, exec, s[58:59]
	s_cbranch_vccnz .LBB0_182
	v_and_b32_e32 v134, 31, v128
	v_mul_u32_u24_e32 v134, 0x70, v134
	v_lshlrev_b64 v[128:129], 7, v[128:129]
	v_sub_u32_e32 v128, v128, v134
	v_cvt_pk_f16_f32 v133, v90, v91
	v_cvt_pk_f16_f32 v132, v88, v89
	v_cvt_pk_f16_f32 v131, v94, v95
	v_cvt_pk_f16_f32 v130, v92, v93
	v_lshl_add_u64 v[128:129], v[154:155], 0, v[128:129]
	global_store_dwordx4 v[128:129], v[130:133], off

; #define GAS __attribute__((address_space(1)))
;     __device__ __forceinline__ void operator()(const f32x4 (&acc)[2][2][4][2], const pg8::Unit& u, int wr, int wc, int fr, int fq) const {
;     ...
;                 for (int m = 0; m < 4; ++m) { const size_t row = (size_t)(row0 + ai * 128 + m * 16);
;                     if (wc < 2) *(GAS h8*)(KI + row * 64 + 32 * wc + 8 * fq) = pack8(acc[ai][0][m][0], acc[ai][0][m][1]);
.LBB0_186:
	s_andn2_b64 vcc, exec, s[58:59]
	s_cbranch_vccnz .LBB0_188
	v_and_b32_e32 v134, 31, v128
	v_mul_u32_u24_e32 v134, 0x70, v134
	v_lshlrev_b64 v[128:129], 7, v[128:129]
	v_sub_u32_e32 v128, v128, v134
	v_cvt_pk_f16_f32 v133, v74, v75
	v_cvt_pk_f16_f32 v132, v72, v73
	v_cvt_pk_f16_f32 v131, v78, v79
	v_cvt_pk_f16_f32 v130, v76, v77
	v_lshl_add_u64 v[128:129], v[154:155], 0, v[128:129]
	global_store_dwordx4 v[128:129], v[130:133], off

; #define GAS __attribute__((address_space(1)))
;     __device__ __forceinline__ void operator()(const f32x4 (&acc)[2][2][4][2], const pg8::Unit& u, int wr, int wc, int fr, int fq) const {
;     ...
;                 for (int m = 0; m < 4; ++m) { const size_t row = (size_t)(row0 + ai * 128 + m * 16);
;                     if (wc < 2) *(GAS h8*)(KI + row * 64 + 32 * wc + 8 * fq) = pack8(acc[ai][0][m][0], acc[ai][0][m][1]);
.LBB0_192:
	s_andn2_b64 vcc, exec, s[58:59]
	s_cbranch_vccnz .LBB0_194
	v_and_b32_e32 v134, 31, v128
	v_mul_u32_u24_e32 v134, 0x70, v134
	v_lshlrev_b64 v[128:129], 7, v[128:129]
	v_sub_u32_e32 v128, v128, v134
	v_cvt_pk_f16_f32 v133, v58, v59
	v_cvt_pk_f16_f32 v132, v56, v57
	v_cvt_pk_f16_f32 v131, v62, v63
	v_cvt_pk_f16_f32 v130, v60, v61
	v_lshl_add_u64 v[128:129], v[154:155], 0, v[128:129]
	global_store_dwordx4 v[128:129], v[130:133], off

; #define GAS __attribute__((address_space(1)))
;     __device__ __forceinline__ void operator()(const f32x4 (&acc)[2][2][4][2], const pg8::Unit& u, int wr, int wc, int fr, int fq) const {
;     ...
;                 for (int m = 0; m < 4; ++m) { const size_t row = (size_t)(row0 + ai * 128 + m * 16);
;                     if (wc < 2) *(GAS h8*)(KI + row * 64 + 32 * wc + 8 * fq) = pack8(acc[ai][0][m][0], acc[ai][0][m][1]);
.LBB0_198:
	s_andn2_b64 vcc, exec, s[58:59]
	s_cbranch_vccnz .LBB0_200
	v_and_b32_e32 v134, 31, v128
	v_mul_u32_u24_e32 v134, 0x70, v134
	v_lshlrev_b64 v[128:129], 7, v[128:129]
	v_sub_u32_e32 v128, v128, v134
	v_cvt_pk_f16_f32 v133, v42, v43
	v_cvt_pk_f16_f32 v132, v40, v41
	v_cvt_pk_f16_f32 v131, v46, v47
	v_cvt_pk_f16_f32 v130, v44, v45
	v_lshl_add_u64 v[128:129], v[154:155], 0, v[128:129]
	global_store_dwordx4 v[128:129], v[130:133], off

; #define GAS __attribute__((address_space(1)))
;     __device__ __forceinline__ void operator()(const f32x4 (&acc)[2][2][4][2], const pg8::Unit& u, int wr, int wc, int fr, int fq) const {
;     ...
;                 for (int m = 0; m < 4; ++m) { const size_t row = (size_t)(row0 + ai * 128 + m * 16);
;                     if (wc < 2) *(GAS h8*)(KI + row * 64 + 32 * wc + 8 * fq) = pack8(acc[ai][0][m][0], acc[ai][0][m][1]);
.LBB0_204:
	s_andn2_b64 vcc, exec, s[58:59]
	s_cbranch_vccnz .LBB0_206
	v_and_b32_e32 v134, 31, v128
	v_mul_u32_u24_e32 v134, 0x70, v134
	v_lshlrev_b64 v[128:129], 7, v[128:129]
	v_sub_u32_e32 v128, v128, v134
	v_cvt_pk_f16_f32 v133, v26, v27
	v_cvt_pk_f16_f32 v132, v24, v25
	v_cvt_pk_f16_f32 v131, v30, v31
	v_cvt_pk_f16_f32 v130, v28, v29
	v_lshl_add_u64 v[128:129], v[154:155], 0, v[128:129]
	global_store_dwordx4 v[128:129], v[130:133], off

; #define GAS __attribute__((address_space(1)))
;     __device__ __forceinline__ void operator()(const f32x4 (&acc)[2][2][4][2], const pg8::Unit& u, int wr, int wc, int fr, int fq) const {
;     ...
;                 for (int m = 0; m < 4; ++m) { const size_t row = (size_t)(row0 + ai * 128 + m * 16);
;                     if (wc < 2) *(GAS h8*)(KI + row * 64 + 32 * wc + 8 * fq) = pack8(acc[ai][0][m][0], acc[ai][0][m][1]);
.LBB0_210:
	s_andn2_b64 vcc, exec, s[8:9]
	s_cbranch_vccnz .LBB0_212
	v_and_b32_e32 v134, 31, v128
	v_mul_u32_u24_e32 v134, 0x70, v134
	v_lshlrev_b64 v[128:129], 7, v[128:129]
	v_sub_u32_e32 v128, v128, v134
	v_cvt_pk_f16_f32 v133, v10, v11
	v_cvt_pk_f16_f32 v132, v8, v9
	v_cvt_pk_f16_f32 v131, v14, v15
	v_cvt_pk_f16_f32 v130, v12, v13
	v_lshl_add_u64 v[128:129], v[154:155], 0, v[128:129]
	global_store_dwordx4 v[128:129], v[130:133], off

; template <int MODE> __device__ __forceinline__ void indexer_item(KP P, LAS unsigned char* lds, int b, int t0, int wave, int lane) {
;     LAS unsigned short* KS = (LAS unsigned short*)lds;
;     const GAS f16* QI = (const GAS f16*)(((GAS unsigned char*)P->ws) + WS_QI); const GAS f16* KI = (const GAS f16*)(((GAS unsigned char*)P->ws) + WS_KI); const GAS float* WI = (const GAS float*)(((GAS unsigned char*)P->ws) + WS_WI);
;     const int ntiles = (t0 + 8 + 31) >> 5, nkp = ntiles * 32;
;     const int n = lane & 31, g = lane >> 5;
;     h8 A[2][4]; float w[2][2][8];
; #pragma unroll
;     for (int mt = 0; mt < 2; ++mt) {
;         const int ql = 2 * ((n >> 2) & 1) + (n >> 4), head = 4 * ((n >> 3) & 1) + (n & 3);
;         const GAS h8* src = (const GAS h8*)(QI + (size_t)(b * SEQ + t0 + 4 * mt + ql) * 512 + head * 64 + 32 * g);
; #pragma unroll
;         for (int kk = 0; kk < 4; ++kk) A[mt][kk] = src[kk];
; #pragma unroll
;         for (int qq = 0; qq < 2; ++qq) { const GAS float* wp = WI + (size_t)(b * SEQ + t0 + 4 * mt + 2 * g + qq) * 8;
;             const f32x4 wa = *(const GAS f32x4*)wp, wb = *(const GAS f32x4*)(wp + 4);
; #pragma unroll
;             for (int h = 0; h < 4; ++h) { w[mt][qq][h] = wa[h]; w[mt][qq][4 + h] = wb[h]; } }
;     }
;     h8 B0a[4], B0b[4], B1a[4], B1b[4];
;     {   const int ta = (wave < ntiles) ? wave : 0, tb = (wave + NW < ntiles) ? wave + NW : ta;
;         const GAS h8* pa = (const GAS h8*)(KI + (size_t)(b * SEQ + ta * 32 + n) * 64 + 32 * g);
;         const GAS h8* pb = (const GAS h8*)(KI + (size_t)(b * SEQ + tb * 32 + n) * 64 + 32 * g);
; #pragma unroll
;         for (int kk = 0; kk < 4; ++kk) { B0a[kk] = pa[kk]; B0b[kk] = pb[kk]; } }
;     for (int tile = wave; tile < ntiles; tile += 4 * NW) {
; template <int MODE> __device__ __forceinline__ void indexer_phase(KP P, LAS unsigned char* lds, int G, int c, int wave, int lane) {
;     *(LAS u32x4*)(lds + 131072 + (wave * 64 + lane) * 16) = (u32x4){0u, 0u, 0u, 0u};
;     __syncthreads();
;     if (G == 256) {
;         for (int rr = 0; rr < 8; ++rr) { const int b = rr >> 2, q = rr & 3;
;             const int blk = (q == 0) ? c : (q == 1) ? 511 - c : (q == 2) ? 512 + c : 1023 - c;
;             if (8 * blk + 7 >= 256) indexer_item<MODE>(P, lds, b, 8 * blk, wave, lane); else causal_masks(P, b, 8 * blk + wave, lane); }
;     } else {
.LBB0_352:
	s_add_i32 s85, s74, 0
	s_add_i32 s3, s85, 0x20000
	s_cmpk_eq_i32 s30, 0x100
	s_barrier
	v_mbcnt_lo_u32_b32 v188, -1, 0
	v_mbcnt_hi_u32_b32 v188, -1, v188
	v_mov_b32_e32 v0, 0
	v_lshlrev_b32_e32 v205, 4, v188
	s_cselect_b64 s[4:5], -1, 0
	s_cmpk_lg_i32 s30, 0x100
	s_mov_b64 s[38:39], s[0:1]
	v_add_u32_e32 v206, s3, v205
	v_mov_b32_e32 v1, v0
	v_mov_b32_e32 v2, v0
	v_mov_b32_e32 v3, v0
	s_cselect_b64 s[44:45], -1, 0
	s_mov_b64 s[6:7], -1
	v_writelane_b32 v248, s4, 7
	s_and_b64 vcc, exec, s[4:5]
	ds_write_b128 v206, v[0:3]
	s_waitcnt lgkmcnt(0)
	s_barrier
	v_writelane_b32 v248, s5, 8
	s_cbranch_vccnz .LBB0_434
	s_cmpk_gt_i32 s2, 0x7ff
	s_cbranch_scc1 .LBB0_433
	v_ashrrev_i32_e32 v1, 5, v188
	v_lshrrev_b32_e32 v0, 1, v188
	v_bfe_u32 v2, v188, 4, 1
	v_ashrrev_i32_e32 v189, 31, v188
	v_and_b32_e32 v208, 31, v188
	v_and_or_b32 v209, v0, 2, v2
	v_and_b32_e32 v2, 3, v188
	v_lshlrev_b32_e32 v210, 1, v1
	s_add_i32 s5, 0, 0x20000
	v_lshlrev_b64 v[4:5], v188, -1
	v_lshlrev_b64 v[190:191], 16, v[188:189]
	v_and_or_b32 v0, v0, 4, v2
	v_and_b32_e32 v2, 0xffffffe0, v188
	v_lshl_add_u32 v212, v1, 11, s5
	v_or_b32_e32 v213, 1, v210
	v_add_u32_e32 v215, 4, v210
	v_add_u32_e32 v217, 5, v210
	s_lshl_b32 s20, s84, 14
	v_not_b32_e32 v189, v5
	v_add_u32_e32 v196, 64, v188
	v_lshl_add_u32 v1, v1, 15, s78
	v_lshlrev_b32_e32 v5, 1, v208
	v_lshlrev_b32_e32 v0, 6, v0
	v_mov_b32_e32 v193, 0
	v_ashrrev_i32_e32 v3, 31, v2
	v_lshl_add_u32 v214, v213, 10, s5
	v_lshl_add_u32 v216, v215, 10, s5
	v_lshl_add_u32 v218, v217, 10, s5
	v_lshlrev_b32_e32 v219, 2, v188
	s_add_i32 s5, s85, 0x22000
	v_not_b32_e32 v194, v4
	v_ashrrev_i32_e32 v197, 31, v196
	v_lshlrev_b32_e32 v4, 3, v196
	v_add3_u32 v1, v1, v5, 0
	s_add_i32 s20, s20, 0
	v_mbcnt_hi_u32_b32 v229, -1, v195
	v_mov_b32_e32 v230, 0x80
	v_cmp_gt_i32_e64 s[6:7], 4, v188
	v_lshlrev_b32_e32 v207, 6, v188
	s_add_i32 s4, s84, 8
	v_lshl_or_b32 v211, s84, 5, v208
	s_mov_b32 s41, 0
	v_lshl_add_u32 v220, v188, 4, s3
	v_cmp_gt_i32_e64 s[8:9], 63, v188
	v_cmp_gt_i32_e64 s[10:11], 62, v188
	v_cmp_gt_i32_e64 s[12:13], 60, v188
	v_cmp_gt_i32_e64 s[14:15], 56, v188
	v_cmp_gt_i32_e64 s[16:17], 48, v188
	v_cmp_gt_i32_e64 s[18:19], 32, v188
	v_or_b32_e32 v221, 3, v219
	v_or_b32_e32 v222, 2, v219
	v_or_b32_e32 v223, 1, v219
	v_lshlrev_b32_e32 v224, 3, v188
	v_lshlrev_b64 v[198:199], 16, v[196:197]
	v_add_u32_e32 v197, 0x10000, v1
	v_add_u32_e32 v225, s20, v205
	v_lshlrev_b32_e32 v192, 1, v0
	v_lshlrev_b64 v[200:201], 1, v[2:3]
	v_lshlrev_b32_e32 v244, 4, v188
	v_mov_b32_e32 v245, 0
	s_mov_b64 s[46:47], 0x7800000
	v_mov_b32_e32 v226, 0x47000080
	s_mov_b32 s33, 0xffff
	v_mov_b32_e32 v227, 1
	s_movk_i32 s42, 0x100
	s_movk_i32 s43, 0xff
	v_add_u32_e32 v228, s5, v4
	v_lshl_or_b32 v231, v229, 2, v230
	v_mov_b32_e32 v240, v193
	v_mov_b32_e32 v241, v193
	v_mov_b32_e32 v242, v193
	v_mov_b32_e32 v243, v193
	v_mov_b32_e32 v232, 0xffffff80
	s_mov_b32 s64, s2
	s_branch .LBB0_357

; #define GAS __attribute__((address_space(1)))
; template <int MODE> __device__ __forceinline__ void indexer_item(KP P, LAS unsigned char* lds, int b, int t0, int wave, int lane) {
;     ...
;     h8 A[2][4]; float w[2][2][8];
; #pragma unroll
;     for (int mt = 0; mt < 2; ++mt) {
;         const int ql = 2 * ((n >> 2) & 1) + (n >> 4), head = 4 * ((n >> 3) & 1) + (n & 3);
;         const GAS h8* src = (const GAS h8*)(QI + (size_t)(b * SEQ + t0 + 4 * mt + ql) * 512 + head * 64 + 32 * g);
; #pragma unroll
;         for (int kk = 0; kk < 4; ++kk) A[mt][kk] = src[kk];
; #pragma unroll
;         for (int qq = 0; qq < 2; ++qq) { const GAS float* wp = WI + (size_t)(b * SEQ + t0 + 4 * mt + 2 * g + qq) * 8;
;             const f32x4 wa = *(const GAS f32x4*)wp, wb = *(const GAS f32x4*)(wp + 4);
; #pragma unroll
;             for (int h = 0; h < 4; ++h) { w[mt][qq][h] = wa[h]; w[mt][qq][4 + h] = wb[h]; } }
;     }
;     h8 B0a[4], B0b[4], B1a[4], B1b[4];
;     {   const int ta = (wave < ntiles) ? wave : 0, tb = (wave + NW < ntiles) ? wave + NW : ta;
;         const GAS h8* pa = (const GAS h8*)(KI + (size_t)(b * SEQ + ta * 32 + n) * 64 + 32 * g);
;         const GAS h8* pb = (const GAS h8*)(KI + (size_t)(b * SEQ + tb * 32 + n) * 64 + 32 * g);
; #pragma unroll
;         for (int kk = 0; kk < 4; ++kk) { B0a[kk] = pa[kk]; B0b[kk] = pb[kk]; } }
.LBB0_362:
	s_load_dwordx2 s[50:51], s[38:39], 0xa8
	s_add_i32 s26, s65, 39
	s_lshr_b32 s22, s26, 5
	s_cmp_ge_u32 s84, s22
	s_cbranch_scc1 .LBB0_370
	s_waitcnt lgkmcnt(0)
	s_add_u32 s20, s50, 0x8a00000
	s_addc_u32 s21, s51, 0
	s_lshl_b32 s25, s48, 13
	s_or_b32 s23, s25, s65
	v_lshl_add_u64 v[0:1], s[50:51], 0, v[192:193]
	v_or_b32_e32 v2, s23, v209
	v_lshl_add_u64 v[0:1], v[0:1], 0, v[200:201]
	v_ashrrev_i32_e32 v3, 31, v2
	v_lshl_add_u64 v[0:1], v[0:1], 0, s[46:47]
	v_lshlrev_b64 v[2:3], 10, v[2:3]
	v_lshl_add_u64 v[2:3], v[0:1], 0, v[2:3]
	global_load_dwordx4 v[60:63], v[2:3], off
	global_load_dwordx4 v[64:67], v[2:3], off offset:16
	global_load_dwordx4 v[68:71], v[2:3], off offset:32
	global_load_dwordx4 v[72:75], v[2:3], off offset:48
	v_add_u32_e32 v2, s23, v210
	v_ashrrev_i32_e32 v3, 31, v2
	v_lshlrev_b64 v[2:3], 5, v[2:3]
	v_lshl_add_u64 v[2:3], s[20:21], 0, v[2:3]
	s_or_b32 s23, s23, 4
	global_load_dwordx4 v[76:79], v[2:3], off
	global_load_dwordx4 v[80:83], v[2:3], off offset:16
	global_load_dwordx4 v[84:87], v[2:3], off offset:32
	global_load_dwordx4 v[88:91], v[2:3], off offset:48
	v_or_b32_e32 v2, s23, v209
	v_ashrrev_i32_e32 v3, 31, v2
	v_lshlrev_b64 v[2:3], 10, v[2:3]
	v_lshl_add_u64 v[0:1], v[0:1], 0, v[2:3]
	global_load_dwordx4 v[92:95], v[0:1], off
	global_load_dwordx4 v[96:99], v[0:1], off offset:16
	global_load_dwordx4 v[100:103], v[0:1], off offset:32
	global_load_dwordx4 v[104:107], v[0:1], off offset:48
	v_add_u32_e32 v0, s23, v210
	v_ashrrev_i32_e32 v1, 31, v0
	v_lshlrev_b64 v[0:1], 5, v[0:1]
	s_add_i32 s23, s22, -8
	s_sub_i32 s24, s22, 24
	v_lshl_add_u64 v[0:1], s[20:21], 0, v[0:1]
	s_add_u32 s20, s50, 0x8800000
	s_addc_u32 s21, s51, 0
	s_cmp_lt_u32 s4, s22
	s_cselect_b32 s27, s4, s84
	s_lshl_b32 s27, s27, 5
	s_add_i32 s27, s27, s25
	global_load_dwordx4 v[108:111], v[0:1], off
	global_load_dwordx4 v[112:115], v[0:1], off offset:16
	global_load_dwordx4 v[116:119], v[0:1], off offset:32
	global_load_dwordx4 v[120:123], v[0:1], off offset:48
	v_mov_b32_e32 v0, s27
	v_ashrrev_i32_e32 v1, 31, v0
	v_lshlrev_b64 v[0:1], 7, v[0:1]
	v_lshl_add_u64 v[0:1], s[20:21], 0, v[0:1]
	v_lshl_add_u64 v[0:1], v[0:1], 0, v[244:245]
	global_load_dwordx4 v[124:127], v[0:1], off
	global_load_dwordx4 v[128:131], v[0:1], off offset:1024
	global_load_dwordx4 v[132:135], v[0:1], off offset:2048
	global_load_dwordx4 v[136:139], v[0:1], off offset:3072
	v_mov_b32_e32 v0, s25
	v_lshl_add_u32 v0, s84, 5, v0
	v_ashrrev_i32_e32 v1, 31, v0
	v_lshlrev_b64 v[0:1], 7, v[0:1]
	v_lshl_add_u64 v[0:1], s[20:21], 0, v[0:1]
	v_lshl_add_u64 v[0:1], v[0:1], 0, v[244:245]
	global_load_dwordx4 v[140:143], v[0:1], off
	global_load_dwordx4 v[144:147], v[0:1], off offset:1024
	global_load_dwordx4 v[148:151], v[0:1], off offset:2048
	global_load_dwordx4 v[152:155], v[0:1], off offset:3072
	v_mov_b32_e32 v233, s25
	v_lshl_add_u64 v[202:203], s[20:21], 0, v[244:245]
	v_add_u32_e32 v234, s65, v210
	v_add_u32_e32 v235, s65, v213
	v_add_u32_e32 v236, s65, v215
	v_add_u32_e32 v237, s65, v217
	v_mov_b32_e32 v238, v197
	v_mov_b32_e32 v239, v211
	s_mov_b32 s25, s84
	s_branch .LBB0_365

; template <int MODE> __device__ __forceinline__ void indexer_pair(LAS unsigned char* lds, const GAS f16* KI, int b, int t0, int ntiles, int tile, int n, int g,
;         const h8 (&A)[2][4], const float (&w)[2][2][8], const h8 (&BA)[4], const h8 (&BB)[4], h8 (&NA)[4], h8 (&NB)[4]) {
;     LAS unsigned short* KS = (LAS unsigned short*)lds;
;         const bool hasB = tile + NW < ntiles;
;         const int tna = (tile + 2 * NW < ntiles) ? tile + 2 * NW : tile, tnb = (tile + 3 * NW < ntiles) ? tile + 3 * NW : tna;
;         const GAS h8* pa = (const GAS h8*)(KI + (size_t)(b * SEQ + tna * 32 + n) * 64 + 32 * g);
;         const GAS h8* pb = (const GAS h8*)(KI + (size_t)(b * SEQ + tnb * 32 + n) * 64 + 32 * g);
;         #pragma unroll
;         for (int kk = 0; kk < 4; ++kk) { NA[kk] = pa[kk]; NB[kk] = pb[kk]; }
;         f32x16 cA[2], cB[2];
; #pragma unroll
;         for (int mt = 0; mt < 2; ++mt) { cA[mt] = __builtin_amdgcn_mfma_f32_32x32x16_f16(A[mt][0], BA[0], f32x16{}, 0, 0, 0); cB[mt] = __builtin_amdgcn_mfma_f32_32x32x16_f16(A[mt][0], BB[0], f32x16{}, 0, 0, 0); }
; #pragma unroll
;         for (int kk = 1; kk < 4; ++kk)
; #pragma unroll
;             for (int mt = 0; mt < 2; ++mt) { cA[mt] = __builtin_amdgcn_mfma_f32_32x32x16_f16(A[mt][kk], BA[kk], cA[mt], 0, 0, 0); cB[mt] = __builtin_amdgcn_mfma_f32_32x32x16_f16(A[mt][kk], BB[kk], cB[mt], 0, 0, 0); }
; #pragma unroll
;         for (int u = 0; u < 2; ++u) {
;             const int s = (tile + u * NW) * 32 + n;
;             if (u == 0 || hasB) {
; #pragma unroll
;                 for (int mt = 0; mt < 2; ++mt)
; #pragma unroll
;                     for (int qq = 0; qq < 2; ++qq) {
;                         float sc = 0.f;
; #pragma unroll
;                         for (int h = 0; h < 8; ++h) sc += w[mt][qq][h] * fmaxf(u ? cB[mt][8 * qq + h] : cA[mt][8 * qq + h], 0.f);
;                         const int ql = 4 * mt + 2 * g + qq;
;                         int key = (int)(sc * 4096.f + 32768.5f);
;                         key = key < 1 ? 1 : (key > 65535 ? 65535 : key);
;                         if (s > t0 + ql) key = 0;
;                         KS[ql * SEQ + s] = (unsigned short)key;
;                         __hip_atomic_fetch_add((LAS unsigned*)(lds + 131072) + ql * 256 + (key >> 8), 1u, __ATOMIC_RELAXED, __HIP_MEMORY_SCOPE_WORKGROUP);
;                     }
;             }
;         }
.LBB0_365:
	s_waitcnt vmcnt(3)
	v_mfma_f32_32x32x16_f16 v[28:43], v[60:63], v[140:143], 0
	s_add_i32 s27, s25, 16
	s_cmp_lt_u32 s27, s22
	s_cselect_b64 s[20:21], -1, 0
	s_and_b64 s[52:53], s[20:21], exec
	s_cselect_b32 s36, s27, s25
	s_add_i32 s37, s25, 24
	s_cmp_lt_u32 s37, s22
	s_waitcnt vmcnt(2)
	v_mfma_f32_32x32x16_f16 v[28:43], v[64:67], v[144:147], v[28:43]
	s_cselect_b32 s37, s37, s36
	v_lshl_add_u32 v0, s36, 5, v233
	v_ashrrev_i32_e32 v1, 31, v0
	v_lshl_add_u32 v2, s37, 5, v233
	v_lshlrev_b64 v[0:1], 7, v[0:1]
	v_ashrrev_i32_e32 v3, 31, v2
	v_lshl_add_u64 v[0:1], v[202:203], 0, v[0:1]
	s_waitcnt vmcnt(1)
	v_mfma_f32_32x32x16_f16 v[28:43], v[68:71], v[148:151], v[28:43]
	v_lshlrev_b64 v[2:3], 7, v[2:3]
	s_waitcnt vmcnt(0)
	v_lshl_add_u64 v[156:157], v[202:203], 0, v[2:3]
	global_load_dwordx4 v[184:187], v[0:1], off
	global_load_dwordx4 v[172:175], v[0:1], off offset:1024
	global_load_dwordx4 v[176:179], v[156:157], off
	global_load_dwordx4 v[168:171], v[156:157], off offset:1024
	global_load_dwordx4 v[164:167], v[0:1], off offset:2048
	global_load_dwordx4 v[160:163], v[0:1], off offset:3072
	global_load_dwordx4 v[180:183], v[156:157], off offset:2048
	s_nop 0
	global_load_dwordx4 v[156:159], v[156:157], off offset:3072
	v_cmp_le_i32_e32 vcc, v239, v234
	s_cmp_ge_i32 s25, s23
	s_waitcnt vmcnt(8)
	v_mfma_f32_32x32x16_f16 v[28:43], v[72:75], v[152:155], v[28:43]
	v_mfma_f32_32x32x16_f16 v[44:59], v[92:95], v[140:143], 0
	s_nop 10
	v_max_f32_e32 v0, v28, v28
	v_max_f32_e32 v1, v29, v29
	v_max_f32_e32 v0, 0, v0
	v_max_f32_e32 v2, v30, v30
	v_max_f32_e32 v1, 0, v1
	v_fma_f32 v0, v76, v0, 0
	v_max_f32_e32 v3, v31, v31
	v_max_f32_e32 v2, 0, v2
	v_fmac_f32_e32 v0, v77, v1
	v_max_f32_e32 v3, 0, v3
	v_fmac_f32_e32 v0, v78, v2
	v_max_f32_e32 v1, v32, v32
	v_fmac_f32_e32 v0, v79, v3
	v_max_f32_e32 v1, 0, v1
	v_fmac_f32_e32 v0, v80, v1
	v_max_f32_e32 v1, v33, v33
	v_max_f32_e32 v1, 0, v1
	v_fmac_f32_e32 v0, v81, v1
	v_max_f32_e32 v1, v34, v34
	v_max_f32_e32 v1, 0, v1
	v_fmac_f32_e32 v0, v82, v1
	v_max_f32_e32 v1, v35, v35
	v_max_f32_e32 v1, 0, v1
	v_fmac_f32_e32 v0, v83, v1
	v_fmamk_f32 v0, v0, 0x45800000, v226
	v_cvt_i32_f32_e32 v32, v0
	v_add_u32_e32 v33, 0xffff0000, v238
	v_mfma_f32_32x32x16_f16 v[44:59], v[96:99], v[144:147], v[44:59]
	v_max_f32_e32 v34, v37, v37
	v_med3_i32 v32, v32, 1, s33
	v_cndmask_b32_e32 v32, 0, v32, vcc
	ds_write_b16 v33, v32
	v_max_f32_e32 v33, v36, v36
	v_max_f32_e32 v33, 0, v33
	v_fma_f32 v33, v84, v33, 0
	v_max_f32_e32 v34, 0, v34
	v_fmac_f32_e32 v33, v85, v34
	v_max_f32_e32 v34, v38, v38
	v_max_f32_e32 v34, 0, v34
	v_fmac_f32_e32 v33, v86, v34
	v_max_f32_e32 v34, v39, v39
	v_max_f32_e32 v34, 0, v34
	v_fmac_f32_e32 v33, v87, v34
	v_max_f32_e32 v34, v40, v40
	v_mfma_f32_32x32x16_f16 v[44:59], v[100:103], v[148:151], v[44:59]
	v_max_f32_e32 v34, 0, v34
	v_fmac_f32_e32 v33, v88, v34
	v_max_f32_e32 v34, v41, v41
	v_max_f32_e32 v34, 0, v34
	v_fmac_f32_e32 v33, v89, v34
	v_max_f32_e32 v34, v42, v42
	v_max_f32_e32 v34, 0, v34
	v_fmac_f32_e32 v33, v90, v34
	v_max_f32_e32 v34, v43, v43
	v_max_f32_e32 v34, 0, v34
	v_fmac_f32_e32 v33, v91, v34
	v_mfma_f32_32x32x16_f16 v[44:59], v[104:107], v[152:155], v[44:59]
	v_fmamk_f32 v33, v33, 0x45800000, v226
	v_cvt_i32_f32_e32 v33, v33
	v_bfe_u32 v32, v32, 8, 8
	v_lshl_add_u32 v32, v32, 2, v212
	ds_add_u32 v32, v227
	v_med3_i32 v32, v33, 1, s33
	v_cmp_le_i32_e32 vcc, v239, v235
	v_add_u32_e32 v33, 0xffff4000, v238
	s_nop 3
	v_max_f32_e32 v34, v45, v45
	v_cndmask_b32_e32 v32, 0, v32, vcc
	ds_write_b16 v33, v32
	v_max_f32_e32 v33, v44, v44
	v_max_f32_e32 v33, 0, v33
	v_fma_f32 v33, v108, v33, 0
	v_max_f32_e32 v34, 0, v34
	v_fmac_f32_e32 v33, v109, v34
	v_max_f32_e32 v34, v46, v46
	v_max_f32_e32 v34, 0, v34
	v_fmac_f32_e32 v33, v110, v34
	v_max_f32_e32 v34, v47, v47
	v_max_f32_e32 v34, 0, v34
	v_fmac_f32_e32 v33, v111, v34
	v_max_f32_e32 v34, v48, v48
	v_max_f32_e32 v34, 0, v34
	v_fmac_f32_e32 v33, v112, v34
	v_max_f32_e32 v34, v49, v49
	v_max_f32_e32 v34, 0, v34
	v_fmac_f32_e32 v33, v113, v34
	v_max_f32_e32 v34, v50, v50
	v_max_f32_e32 v34, 0, v34
	v_fmac_f32_e32 v33, v114, v34
	v_max_f32_e32 v34, v51, v51
	v_max_f32_e32 v34, 0, v34
	v_fmac_f32_e32 v33, v115, v34
	v_fmamk_f32 v33, v33, 0x45800000, v226
	v_cvt_i32_f32_e32 v33, v33
	v_mfma_f32_32x32x16_f16 v[16:31], v[60:63], v[124:127], 0
	v_bfe_u32 v32, v32, 8, 8
	v_lshl_add_u32 v32, v32, 2, v214
	ds_add_u32 v32, v227
	v_med3_i32 v32, v33, 1, s33
	v_max_f32_e32 v33, v52, v52
	v_max_f32_e32 v33, 0, v33
	v_max_f32_e32 v34, v53, v53
	v_mfma_f32_32x32x16_f16 v[0:15], v[92:95], v[124:127], 0
	v_fma_f32 v33, v116, v33, 0
	v_max_f32_e32 v34, 0, v34
	v_fmac_f32_e32 v33, v117, v34
	v_max_f32_e32 v34, v54, v54
	v_max_f32_e32 v34, 0, v34
	v_fmac_f32_e32 v33, v118, v34
	v_max_f32_e32 v34, v55, v55
	v_mfma_f32_32x32x16_f16 v[16:31], v[64:67], v[128:131], v[16:31]
	v_max_f32_e32 v34, 0, v34
	v_fmac_f32_e32 v33, v119, v34
	v_max_f32_e32 v34, v56, v56
	v_max_f32_e32 v34, 0, v34
	v_fmac_f32_e32 v33, v120, v34
	v_max_f32_e32 v34, v57, v57
	v_max_f32_e32 v34, 0, v34
	v_mfma_f32_32x32x16_f16 v[0:15], v[96:99], v[128:131], v[0:15]
	v_fmac_f32_e32 v33, v121, v34
	v_max_f32_e32 v34, v58, v58
	v_max_f32_e32 v34, 0, v34
	v_fmac_f32_e32 v33, v122, v34
	v_max_f32_e32 v34, v59, v59
	v_max_f32_e32 v34, 0, v34
	v_fmac_f32_e32 v33, v123, v34
	v_mfma_f32_32x32x16_f16 v[16:31], v[68:71], v[132:135], v[16:31]
	v_fmamk_f32 v33, v33, 0x45800000, v226
	v_cmp_le_i32_e32 vcc, v239, v236
	v_cvt_i32_f32_e32 v33, v33
	s_nop 0
	v_cndmask_b32_e32 v32, 0, v32, vcc
	ds_write_b16 v238, v32
	v_bfe_u32 v32, v32, 8, 8
	v_mfma_f32_32x32x16_f16 v[0:15], v[100:103], v[132:135], v[0:15]
	v_lshl_add_u32 v32, v32, 2, v216
	ds_add_u32 v32, v227
	v_med3_i32 v32, v33, 1, s33
	v_cmp_le_i32_e32 vcc, v239, v237
	s_nop 1
	v_cndmask_b32_e32 v32, 0, v32, vcc
	v_mfma_f32_32x32x16_f16 v[16:31], v[72:75], v[136:139], v[16:31]
	ds_write_b16 v238, v32 offset:16384
	v_bfe_u32 v32, v32, 8, 8
	v_lshl_add_u32 v32, v32, 2, v218
	ds_add_u32 v32, v227
	v_mfma_f32_32x32x16_f16 v[0:15], v[104:107], v[136:139], v[0:15]
	s_cbranch_scc1 .LBB0_367
; #define LAS __attribute__((address_space(3)))
; template <int MODE> __device__ __forceinline__ void indexer_pair(LAS unsigned char* lds, const GAS f16* KI, int b, int t0, int ntiles, int tile, int n, int g,
;         const h8 (&A)[2][4], const float (&w)[2][2][8], const h8 (&BA)[4], const h8 (&BB)[4], h8 (&NA)[4], h8 (&NB)[4]) {
;     ...
; #pragma unroll
;         for (int u = 0; u < 2; ++u) {
;             const int s = (tile + u * NW) * 32 + n;
;             if (u == 0 || hasB) {
; #pragma unroll
;                 for (int mt = 0; mt < 2; ++mt)
; #pragma unroll
;                     for (int qq = 0; qq < 2; ++qq) {
;                         float sc = 0.f;
; #pragma unroll
;                         for (int h = 0; h < 8; ++h) sc += w[mt][qq][h] * fmaxf(u ? cB[mt][8 * qq + h] : cA[mt][8 * qq + h], 0.f);
;                         const int ql = 4 * mt + 2 * g + qq;
;                         int key = (int)(sc * 4096.f + 32768.5f);
;                         key = key < 1 ? 1 : (key > 65535 ? 65535 : key);
;                         if (s > t0 + ql) key = 0;
;                         KS[ql * SEQ + s] = (unsigned short)key;
;                         __hip_atomic_fetch_add((LAS unsigned*)(lds + 131072) + ql * 256 + (key >> 8), 1u, __ATOMIC_RELAXED, __HIP_MEMORY_SCOPE_WORKGROUP);
;                     }
;             }
;         }
; template <int MODE> __device__ __forceinline__ void indexer_item(KP P, LAS unsigned char* lds, int b, int t0, int wave, int lane) {
;     ...
;     for (int tile = wave; tile < ntiles; tile += 4 * NW) {
;         indexer_pair<MODE>(lds, KI, b, t0, ntiles, tile, n, g, A, w, B0a, B0b, B1a, B1b);
;         if (tile + 2 * NW < ntiles) indexer_pair<MODE>(lds, KI, b, t0, ntiles, tile + 2 * NW, n, g, A, w, B1a, B1b, B0a, B0b);
;     }
	s_nop 5
	v_max_f32_e32 v16, v16, v16
	v_max_f32_e32 v16, 0, v16
	v_max_f32_e32 v17, v17, v17
	v_fma_f32 v16, v76, v16, 0
	v_max_f32_e32 v17, 0, v17
	v_fmac_f32_e32 v16, v77, v17
	v_max_f32_e32 v17, v18, v18
	v_max_f32_e32 v17, 0, v17
	v_fmac_f32_e32 v16, v78, v17
	v_max_f32_e32 v17, v19, v19
	v_max_f32_e32 v17, 0, v17
	v_fmac_f32_e32 v16, v79, v17
	v_max_f32_e32 v17, v20, v20
	v_max_f32_e32 v17, 0, v17
	v_fmac_f32_e32 v16, v80, v17
	v_max_f32_e32 v17, v21, v21
	v_max_f32_e32 v17, 0, v17
	v_fmac_f32_e32 v16, v81, v17
	v_max_f32_e32 v17, v22, v22
	v_max_f32_e32 v17, 0, v17
	v_fmac_f32_e32 v16, v82, v17
	v_max_f32_e32 v17, v23, v23
	v_max_f32_e32 v17, 0, v17
	v_fmac_f32_e32 v16, v83, v17
	v_fmamk_f32 v16, v16, 0x45800000, v226
	v_cvt_i32_f32_e32 v16, v16
	v_add_u32_e32 v17, 0x100, v239
	v_cmp_le_i32_e32 vcc, v17, v234
	v_add_u32_e32 v18, 0xffff0200, v238
	v_med3_i32 v16, v16, 1, s33
	v_cndmask_b32_e32 v16, 0, v16, vcc
	ds_write_b16 v18, v16
	v_max_f32_e32 v18, v24, v24
	v_max_f32_e32 v18, 0, v18
	v_max_f32_e32 v19, v25, v25
	v_fma_f32 v18, v84, v18, 0
	v_max_f32_e32 v19, 0, v19
	v_fmac_f32_e32 v18, v85, v19
	v_max_f32_e32 v19, v26, v26
	v_max_f32_e32 v19, 0, v19
	v_fmac_f32_e32 v18, v86, v19
	v_max_f32_e32 v19, v27, v27
	v_max_f32_e32 v19, 0, v19
	v_fmac_f32_e32 v18, v87, v19
	v_max_f32_e32 v19, v28, v28
	v_max_f32_e32 v19, 0, v19
	v_max_f32_e32 v0, v0, v0
	v_fmac_f32_e32 v18, v88, v19
	v_max_f32_e32 v19, v29, v29
	v_max_f32_e32 v0, 0, v0
	v_max_f32_e32 v1, v1, v1
	v_max_f32_e32 v19, 0, v19
	v_fma_f32 v0, v108, v0, 0
	v_max_f32_e32 v1, 0, v1
	v_fmac_f32_e32 v18, v89, v19
	v_max_f32_e32 v19, v30, v30
	v_fmac_f32_e32 v0, v109, v1
	v_max_f32_e32 v1, v2, v2
	v_max_f32_e32 v19, 0, v19
	v_max_f32_e32 v1, 0, v1
	v_fmac_f32_e32 v18, v90, v19
	v_max_f32_e32 v19, v31, v31
	v_fmac_f32_e32 v0, v110, v1
	v_max_f32_e32 v1, v3, v3
	v_max_f32_e32 v19, 0, v19
	v_max_f32_e32 v1, 0, v1
	v_fmac_f32_e32 v18, v91, v19
	v_fmac_f32_e32 v0, v111, v1
	v_max_f32_e32 v1, v4, v4
	v_fmamk_f32 v18, v18, 0x45800000, v226
	v_max_f32_e32 v1, 0, v1
	v_cvt_i32_f32_e32 v18, v18
	v_fmac_f32_e32 v0, v112, v1
	v_max_f32_e32 v1, v5, v5
	v_max_f32_e32 v1, 0, v1
	v_bfe_u32 v16, v16, 8, 8
	v_fmac_f32_e32 v0, v113, v1
	v_max_f32_e32 v1, v6, v6
	v_lshl_add_u32 v16, v16, 2, v212
	v_max_f32_e32 v1, 0, v1
	ds_add_u32 v16, v227
	v_med3_i32 v16, v18, 1, s33
	v_cmp_le_i32_e32 vcc, v17, v235
	v_fmac_f32_e32 v0, v114, v1
	v_max_f32_e32 v1, v7, v7
	v_cndmask_b32_e32 v16, 0, v16, vcc
	v_max_f32_e32 v1, 0, v1
	v_add_u32_e32 v18, 0xffff4200, v238
	v_fmac_f32_e32 v0, v115, v1
	v_bfe_u32 v1, v16, 8, 8
	ds_write_b16 v18, v16
	v_lshl_add_u32 v1, v1, 2, v214
	ds_add_u32 v1, v227
	v_max_f32_e32 v1, v8, v8
	v_max_f32_e32 v1, 0, v1
	v_max_f32_e32 v2, v9, v9
	v_fma_f32 v1, v116, v1, 0
	v_max_f32_e32 v2, 0, v2
	v_fmac_f32_e32 v1, v117, v2
	v_max_f32_e32 v2, v10, v10
	v_max_f32_e32 v2, 0, v2
	v_fmac_f32_e32 v1, v118, v2
	v_max_f32_e32 v2, v11, v11
	v_max_f32_e32 v2, 0, v2
	v_fmac_f32_e32 v1, v119, v2
	v_max_f32_e32 v2, v12, v12
	v_max_f32_e32 v2, 0, v2
	v_fmac_f32_e32 v1, v120, v2
	v_max_f32_e32 v2, v13, v13
	v_max_f32_e32 v2, 0, v2
	v_fmac_f32_e32 v1, v121, v2
	v_max_f32_e32 v2, v14, v14
	v_fmamk_f32 v0, v0, 0x45800000, v226
	v_max_f32_e32 v2, 0, v2
	v_cvt_i32_f32_e32 v0, v0
	v_fmac_f32_e32 v1, v122, v2
	v_max_f32_e32 v2, v15, v15
	v_max_f32_e32 v2, 0, v2
	v_fmac_f32_e32 v1, v123, v2
	v_fmamk_f32 v1, v1, 0x45800000, v226
	v_med3_i32 v0, v0, 1, s33
	v_cmp_le_i32_e32 vcc, v17, v236
	v_cvt_i32_f32_e32 v1, v1
	s_nop 0
	v_cndmask_b32_e32 v0, 0, v0, vcc
	ds_write_b16 v238, v0 offset:512
	v_bfe_u32 v0, v0, 8, 8
	v_lshl_add_u32 v0, v0, 2, v216
	ds_add_u32 v0, v227
	v_med3_i32 v0, v1, 1, s33
	v_cmp_le_i32_e32 vcc, v17, v237
	s_nop 1
	v_cndmask_b32_e32 v0, 0, v0, vcc
	ds_write_b16 v238, v0 offset:16896
	v_bfe_u32 v0, v0, 8, 8
	v_lshl_add_u32 v0, v0, 2, v218
	ds_add_u32 v0, v227
.LBB0_367:
	s_andn2_b64 vcc, exec, s[20:21]
	s_add_i32 s20, s25, 32
	s_cbranch_vccnz .LBB0_364
	s_waitcnt vmcnt(7)
	v_mfma_f32_32x32x16_f16 v[42:57], v[60:63], v[184:187], 0
	s_cmp_lt_u32 s20, s22
	s_cselect_b32 s21, s20, s27
	s_add_i32 s27, s25, 40
	s_cmp_lt_u32 s27, s22
	s_nop 1
	v_lshl_add_u32 v0, s21, 5, v233
	s_cselect_b32 s21, s27, s21
	v_ashrrev_i32_e32 v1, 31, v0
	s_waitcnt vmcnt(6)
	v_mfma_f32_32x32x16_f16 v[42:57], v[64:67], v[172:175], v[42:57]
	v_lshl_add_u32 v2, s21, 5, v233
	v_lshlrev_b64 v[0:1], 7, v[0:1]
	v_ashrrev_i32_e32 v3, 31, v2
	v_lshl_add_u64 v[0:1], v[202:203], 0, v[0:1]
	v_lshlrev_b64 v[2:3], 7, v[2:3]
	v_lshl_add_u64 v[2:3], v[202:203], 0, v[2:3]
	global_load_dwordx4 v[140:143], v[0:1], off
	global_load_dwordx4 v[144:147], v[0:1], off offset:1024
	global_load_dwordx4 v[124:127], v[2:3], off
	global_load_dwordx4 v[128:131], v[2:3], off offset:1024
	global_load_dwordx4 v[148:151], v[0:1], off offset:2048
	global_load_dwordx4 v[152:155], v[0:1], off offset:3072
	global_load_dwordx4 v[132:135], v[2:3], off offset:2048
	global_load_dwordx4 v[136:139], v[2:3], off offset:3072
	s_waitcnt vmcnt(11)
	v_mfma_f32_32x32x16_f16 v[42:57], v[68:71], v[164:167], v[42:57]
	v_add_u32_e32 v58, 0xffff0400, v238
	s_cmp_ge_i32 s25, s24
	s_waitcnt vmcnt(10)
; #define LAS __attribute__((address_space(3)))
; template <int MODE> __device__ __forceinline__ void indexer_pair(LAS unsigned char* lds, const GAS f16* KI, int b, int t0, int ntiles, int tile, int n, int g,
;         const h8 (&A)[2][4], const float (&w)[2][2][8], const h8 (&BA)[4], const h8 (&BB)[4], h8 (&NA)[4], h8 (&NB)[4]) {
;     ...
;         for (int mt = 0; mt < 2; ++mt) { cA[mt] = __builtin_amdgcn_mfma_f32_32x32x16_f16(A[mt][0], BA[0], f32x16{}, 0, 0, 0); cB[mt] = __builtin_amdgcn_mfma_f32_32x32x16_f16(A[mt][0], BB[0], f32x16{}, 0, 0, 0); }
; #pragma unroll
;         for (int kk = 1; kk < 4; ++kk)
; #pragma unroll
;             for (int mt = 0; mt < 2; ++mt) { cA[mt] = __builtin_amdgcn_mfma_f32_32x32x16_f16(A[mt][kk], BA[kk], cA[mt], 0, 0, 0); cB[mt] = __builtin_amdgcn_mfma_f32_32x32x16_f16(A[mt][kk], BB[kk], cB[mt], 0, 0, 0); }
; #pragma unroll
;         for (int u = 0; u < 2; ++u) {
;             const int s = (tile + u * NW) * 32 + n;
;             if (u == 0 || hasB) {
; #pragma unroll
;                 for (int mt = 0; mt < 2; ++mt)
; #pragma unroll
;                     for (int qq = 0; qq < 2; ++qq) {
;                         float sc = 0.f;
; #pragma unroll
;                         for (int h = 0; h < 8; ++h) sc += w[mt][qq][h] * fmaxf(u ? cB[mt][8 * qq + h] : cA[mt][8 * qq + h], 0.f);
;                         const int ql = 4 * mt + 2 * g + qq;
;                         int key = (int)(sc * 4096.f + 32768.5f);
;                         key = key < 1 ? 1 : (key > 65535 ? 65535 : key);
;                         if (s > t0 + ql) key = 0;
;                         KS[ql * SEQ + s] = (unsigned short)key;
;                         __hip_atomic_fetch_add((LAS unsigned*)(lds + 131072) + ql * 256 + (key >> 8), 1u, __ATOMIC_RELAXED, __HIP_MEMORY_SCOPE_WORKGROUP);
;                     }
;             }
;         }
	v_mfma_f32_32x32x16_f16 v[42:57], v[72:75], v[160:163], v[42:57]
	v_mfma_f32_32x32x16_f16 v[16:31], v[60:63], v[176:179], 0
	s_nop 10
	v_max_f32_e32 v0, v42, v42
	v_max_f32_e32 v1, v43, v43
	v_max_f32_e32 v0, 0, v0
	v_max_f32_e32 v2, v44, v44
	v_max_f32_e32 v1, 0, v1
	v_fma_f32 v0, v76, v0, 0
	v_max_f32_e32 v3, v45, v45
	v_max_f32_e32 v2, 0, v2
	v_fmac_f32_e32 v0, v77, v1
	v_max_f32_e32 v4, v46, v46
	v_max_f32_e32 v3, 0, v3
	v_fmac_f32_e32 v0, v78, v2
	v_fmac_f32_e32 v0, v79, v3
	v_max_f32_e32 v1, 0, v4
	v_fmac_f32_e32 v0, v80, v1
	v_max_f32_e32 v1, v47, v47
	v_mfma_f32_32x32x16_f16 v[32:47], v[92:95], v[184:187], 0
	v_max_f32_e32 v1, 0, v1
	v_fmac_f32_e32 v0, v81, v1
	v_max_f32_e32 v1, v48, v48
	v_max_f32_e32 v1, 0, v1
	v_fmac_f32_e32 v0, v82, v1
	v_max_f32_e32 v1, v49, v49
	v_max_f32_e32 v1, 0, v1
	v_mfma_f32_32x32x16_f16 v[32:47], v[96:99], v[172:175], v[32:47]
	v_fmac_f32_e32 v0, v83, v1
	v_fmamk_f32 v0, v0, 0x45800000, v226
	v_cvt_i32_f32_e32 v48, v0
	v_add_u32_e32 v49, 0x200, v239
	v_cmp_le_i32_e32 vcc, v49, v234
	v_med3_i32 v48, v48, 1, s33
	v_mfma_f32_32x32x16_f16 v[32:47], v[100:103], v[164:167], v[32:47]
	v_cndmask_b32_e32 v48, 0, v48, vcc
	ds_write_b16 v58, v48
	v_bfe_u32 v48, v48, 8, 8
	v_lshl_add_u32 v48, v48, 2, v212
	ds_add_u32 v48, v227
	v_max_f32_e32 v48, v50, v50
	v_max_f32_e32 v48, 0, v48
	v_mfma_f32_32x32x16_f16 v[32:47], v[104:107], v[160:163], v[32:47]
	v_max_f32_e32 v50, v51, v51
	v_fma_f32 v48, v84, v48, 0
	v_max_f32_e32 v50, 0, v50
	v_fmac_f32_e32 v48, v85, v50
	v_max_f32_e32 v50, v52, v52
	v_max_f32_e32 v50, 0, v50
	v_fmac_f32_e32 v48, v86, v50
	v_max_f32_e32 v50, v53, v53
	v_max_f32_e32 v50, 0, v50
	v_fmac_f32_e32 v48, v87, v50
	v_max_f32_e32 v50, v54, v54
	v_max_f32_e32 v50, 0, v50
	v_max_f32_e32 v32, v32, v32
	v_fmac_f32_e32 v48, v88, v50
	v_max_f32_e32 v50, v55, v55
	v_max_f32_e32 v32, 0, v32
	v_max_f32_e32 v33, v33, v33
	v_max_f32_e32 v50, 0, v50
	v_fma_f32 v32, v108, v32, 0
	v_max_f32_e32 v33, 0, v33
	v_fmac_f32_e32 v48, v89, v50
	v_max_f32_e32 v50, v56, v56
	v_fmac_f32_e32 v32, v109, v33
	v_max_f32_e32 v33, v34, v34
	v_max_f32_e32 v50, 0, v50
	v_max_f32_e32 v33, 0, v33
	v_fmac_f32_e32 v48, v90, v50
	v_max_f32_e32 v50, v57, v57
	v_fmac_f32_e32 v32, v110, v33
	v_max_f32_e32 v33, v35, v35
	v_max_f32_e32 v50, 0, v50
	v_max_f32_e32 v33, 0, v33
	v_fmac_f32_e32 v48, v91, v50
	v_fmac_f32_e32 v32, v111, v33
	v_max_f32_e32 v33, v36, v36
	v_fmamk_f32 v48, v48, 0x45800000, v226
	v_max_f32_e32 v33, 0, v33
	v_cvt_i32_f32_e32 v48, v48
	v_fmac_f32_e32 v32, v112, v33
	v_max_f32_e32 v33, v37, v37
	v_max_f32_e32 v33, 0, v33
	v_fmac_f32_e32 v32, v113, v33
	v_max_f32_e32 v33, v38, v38
	v_max_f32_e32 v33, 0, v33
	v_med3_i32 v48, v48, 1, s33
	v_cmp_le_i32_e32 vcc, v49, v235
	v_fmac_f32_e32 v32, v114, v33
	v_max_f32_e32 v33, v39, v39
	v_mfma_f32_32x32x16_f16 v[0:15], v[92:95], v[176:179], 0
	v_cndmask_b32_e32 v48, 0, v48, vcc
	v_max_f32_e32 v33, 0, v33
	v_add_u32_e32 v50, 0xffff4400, v238
	v_fmac_f32_e32 v32, v115, v33
	v_bfe_u32 v33, v48, 8, 8
	ds_write_b16 v50, v48
	v_lshl_add_u32 v33, v33, 2, v214
	ds_add_u32 v33, v227
	v_max_f32_e32 v33, v40, v40
	v_max_f32_e32 v33, 0, v33
	v_max_f32_e32 v34, v41, v41
	v_fma_f32 v33, v116, v33, 0
	v_max_f32_e32 v34, 0, v34
	v_fmac_f32_e32 v33, v117, v34
	v_max_f32_e32 v34, v42, v42
	v_max_f32_e32 v34, 0, v34
	v_mfma_f32_32x32x16_f16 v[16:31], v[64:67], v[168:171], v[16:31]
	v_fmac_f32_e32 v33, v118, v34
	v_max_f32_e32 v34, v43, v43
	v_max_f32_e32 v34, 0, v34
	v_fmac_f32_e32 v33, v119, v34
	v_max_f32_e32 v34, v44, v44
	v_max_f32_e32 v34, 0, v34
	v_fmac_f32_e32 v33, v120, v34
	v_mfma_f32_32x32x16_f16 v[0:15], v[96:99], v[168:171], v[0:15]
	v_max_f32_e32 v34, v45, v45
	v_max_f32_e32 v34, 0, v34
	v_fmac_f32_e32 v33, v121, v34
	v_max_f32_e32 v34, v46, v46
	v_fmamk_f32 v32, v32, 0x45800000, v226
	v_max_f32_e32 v34, 0, v34
	v_cvt_i32_f32_e32 v32, v32
	s_waitcnt vmcnt(9)
	v_mfma_f32_32x32x16_f16 v[16:31], v[68:71], v[180:183], v[16:31]
	v_fmac_f32_e32 v33, v122, v34
	v_max_f32_e32 v34, v47, v47
	v_max_f32_e32 v34, 0, v34
	v_fmac_f32_e32 v33, v123, v34
	v_fmamk_f32 v33, v33, 0x45800000, v226
	v_med3_i32 v32, v32, 1, s33
	v_cmp_le_i32_e32 vcc, v49, v236
	v_mfma_f32_32x32x16_f16 v[0:15], v[100:103], v[180:183], v[0:15]
	v_cvt_i32_f32_e32 v33, v33
	v_cndmask_b32_e32 v32, 0, v32, vcc
	ds_write_b16 v238, v32 offset:1024
	v_bfe_u32 v32, v32, 8, 8
	v_lshl_add_u32 v32, v32, 2, v216
	ds_add_u32 v32, v227
	v_med3_i32 v32, v33, 1, s33
	s_waitcnt vmcnt(8)
	v_mfma_f32_32x32x16_f16 v[16:31], v[72:75], v[156:159], v[16:31]
	v_cmp_le_i32_e32 vcc, v49, v237
	s_nop 1
	v_cndmask_b32_e32 v32, 0, v32, vcc
	ds_write_b16 v238, v32 offset:17408
	v_bfe_u32 v32, v32, 8, 8
	v_lshl_add_u32 v32, v32, 2, v218
	v_mfma_f32_32x32x16_f16 v[0:15], v[104:107], v[156:159], v[0:15]
	ds_add_u32 v32, v227
	s_cbranch_scc1 .LBB0_364
; #define LAS __attribute__((address_space(3)))
; template <int MODE> __device__ __forceinline__ void indexer_pair(LAS unsigned char* lds, const GAS f16* KI, int b, int t0, int ntiles, int tile, int n, int g,
;         const h8 (&A)[2][4], const float (&w)[2][2][8], const h8 (&BA)[4], const h8 (&BB)[4], h8 (&NA)[4], h8 (&NB)[4]) {
;     ...
; #pragma unroll
;         for (int u = 0; u < 2; ++u) {
;             const int s = (tile + u * NW) * 32 + n;
;             if (u == 0 || hasB) {
; #pragma unroll
;                 for (int mt = 0; mt < 2; ++mt)
; #pragma unroll
;                     for (int qq = 0; qq < 2; ++qq) {
;                         float sc = 0.f;
; #pragma unroll
;                         for (int h = 0; h < 8; ++h) sc += w[mt][qq][h] * fmaxf(u ? cB[mt][8 * qq + h] : cA[mt][8 * qq + h], 0.f);
;                         const int ql = 4 * mt + 2 * g + qq;
;                         int key = (int)(sc * 4096.f + 32768.5f);
;                         key = key < 1 ? 1 : (key > 65535 ? 65535 : key);
;                         if (s > t0 + ql) key = 0;
;                         KS[ql * SEQ + s] = (unsigned short)key;
;                         __hip_atomic_fetch_add((LAS unsigned*)(lds + 131072) + ql * 256 + (key >> 8), 1u, __ATOMIC_RELAXED, __HIP_MEMORY_SCOPE_WORKGROUP);
;                     }
;             }
;         }
	s_nop 1
	v_max_f32_e32 v16, v16, v16
	v_max_f32_e32 v16, 0, v16
	v_max_f32_e32 v17, v17, v17
	v_fma_f32 v16, v76, v16, 0
	v_max_f32_e32 v17, 0, v17
	v_fmac_f32_e32 v16, v77, v17
	v_max_f32_e32 v17, v18, v18
	v_max_f32_e32 v17, 0, v17
	v_fmac_f32_e32 v16, v78, v17
	v_max_f32_e32 v17, v19, v19
	v_max_f32_e32 v17, 0, v17
	v_fmac_f32_e32 v16, v79, v17
	v_max_f32_e32 v17, v20, v20
	v_max_f32_e32 v17, 0, v17
	v_fmac_f32_e32 v16, v80, v17
	v_max_f32_e32 v17, v21, v21
	v_max_f32_e32 v17, 0, v17
	v_fmac_f32_e32 v16, v81, v17
	v_max_f32_e32 v17, v22, v22
	v_max_f32_e32 v17, 0, v17
	v_fmac_f32_e32 v16, v82, v17
	v_max_f32_e32 v17, v23, v23
	v_max_f32_e32 v17, 0, v17
	v_fmac_f32_e32 v16, v83, v17
	v_fmamk_f32 v16, v16, 0x45800000, v226
	v_cvt_i32_f32_e32 v16, v16
	v_add_u32_e32 v17, 0x300, v239
	v_cmp_le_i32_e32 vcc, v17, v234
	v_add_u32_e32 v18, 0xffff0600, v238
	v_med3_i32 v16, v16, 1, s33
	v_cndmask_b32_e32 v16, 0, v16, vcc
	ds_write_b16 v18, v16
	v_max_f32_e32 v18, v24, v24
	v_max_f32_e32 v18, 0, v18
	v_max_f32_e32 v19, v25, v25
	v_fma_f32 v18, v84, v18, 0
	v_max_f32_e32 v19, 0, v19
	v_fmac_f32_e32 v18, v85, v19
	v_max_f32_e32 v19, v26, v26
	v_max_f32_e32 v19, 0, v19
	v_fmac_f32_e32 v18, v86, v19
	v_max_f32_e32 v19, v27, v27
	v_max_f32_e32 v19, 0, v19
	v_fmac_f32_e32 v18, v87, v19
	v_max_f32_e32 v19, v28, v28
	v_max_f32_e32 v19, 0, v19
	v_max_f32_e32 v0, v0, v0
	v_fmac_f32_e32 v18, v88, v19
	v_max_f32_e32 v19, v29, v29
	v_max_f32_e32 v0, 0, v0
	v_max_f32_e32 v1, v1, v1
	v_max_f32_e32 v19, 0, v19
	v_fma_f32 v0, v108, v0, 0
	v_max_f32_e32 v1, 0, v1
	v_fmac_f32_e32 v18, v89, v19
	v_max_f32_e32 v19, v30, v30
	v_fmac_f32_e32 v0, v109, v1
	v_max_f32_e32 v1, v2, v2
	v_max_f32_e32 v19, 0, v19
	v_max_f32_e32 v1, 0, v1
	v_fmac_f32_e32 v18, v90, v19
	v_max_f32_e32 v19, v31, v31
	v_fmac_f32_e32 v0, v110, v1
	v_max_f32_e32 v1, v3, v3
	v_max_f32_e32 v19, 0, v19
	v_max_f32_e32 v1, 0, v1
	v_fmac_f32_e32 v18, v91, v19
	v_fmac_f32_e32 v0, v111, v1
	v_max_f32_e32 v1, v4, v4
	v_fmamk_f32 v18, v18, 0x45800000, v226
	v_max_f32_e32 v1, 0, v1
	v_cvt_i32_f32_e32 v18, v18
	v_fmac_f32_e32 v0, v112, v1
	v_max_f32_e32 v1, v5, v5
	v_max_f32_e32 v1, 0, v1
	v_bfe_u32 v16, v16, 8, 8
	v_fmac_f32_e32 v0, v113, v1
	v_max_f32_e32 v1, v6, v6
	v_lshl_add_u32 v16, v16, 2, v212
	v_max_f32_e32 v1, 0, v1
	ds_add_u32 v16, v227
	v_med3_i32 v16, v18, 1, s33
	v_cmp_le_i32_e32 vcc, v17, v235
	v_fmac_f32_e32 v0, v114, v1
	v_max_f32_e32 v1, v7, v7
	v_cndmask_b32_e32 v16, 0, v16, vcc
	v_max_f32_e32 v1, 0, v1
	v_add_u32_e32 v18, 0xffff4600, v238
	v_fmac_f32_e32 v0, v115, v1
	v_bfe_u32 v1, v16, 8, 8
	ds_write_b16 v18, v16
	v_lshl_add_u32 v1, v1, 2, v214
	ds_add_u32 v1, v227
	v_max_f32_e32 v1, v8, v8
	v_max_f32_e32 v1, 0, v1
	v_max_f32_e32 v2, v9, v9
	v_fma_f32 v1, v116, v1, 0
	v_max_f32_e32 v2, 0, v2
	v_fmac_f32_e32 v1, v117, v2
	v_max_f32_e32 v2, v10, v10
	v_max_f32_e32 v2, 0, v2
	v_fmac_f32_e32 v1, v118, v2
	v_max_f32_e32 v2, v11, v11
	v_max_f32_e32 v2, 0, v2
	v_fmac_f32_e32 v1, v119, v2
	v_max_f32_e32 v2, v12, v12
	v_max_f32_e32 v2, 0, v2
	v_fmac_f32_e32 v1, v120, v2
	v_max_f32_e32 v2, v13, v13
	v_max_f32_e32 v2, 0, v2
	v_fmac_f32_e32 v1, v121, v2
	v_max_f32_e32 v2, v14, v14
	v_fmamk_f32 v0, v0, 0x45800000, v226
	v_max_f32_e32 v2, 0, v2
	v_cvt_i32_f32_e32 v0, v0
	v_fmac_f32_e32 v1, v122, v2
	v_max_f32_e32 v2, v15, v15
	v_max_f32_e32 v2, 0, v2
	v_fmac_f32_e32 v1, v123, v2
	v_fmamk_f32 v1, v1, 0x45800000, v226
	v_med3_i32 v0, v0, 1, s33
	v_cmp_le_i32_e32 vcc, v17, v236
	v_cvt_i32_f32_e32 v1, v1
	s_nop 0
	v_cndmask_b32_e32 v0, 0, v0, vcc
	ds_write_b16 v238, v0 offset:1536
	v_bfe_u32 v0, v0, 8, 8
	v_lshl_add_u32 v0, v0, 2, v216
	ds_add_u32 v0, v227
	v_med3_i32 v0, v1, 1, s33
	v_cmp_le_i32_e32 vcc, v17, v237
	s_nop 1
	v_cndmask_b32_e32 v0, 0, v0, vcc
	ds_write_b16 v238, v0 offset:17920
	v_bfe_u32 v0, v0, 8, 8
	v_lshl_add_u32 v0, v0, 2, v218
	ds_add_u32 v0, v227
	s_branch .LBB0_364

; #define LAS __attribute__((address_space(3)))
; template <int MODE> __device__ __forceinline__ void indexer_item(KP P, LAS unsigned char* lds, int b, int t0, int wave, int lane) {
;     LAS unsigned short* KS = (LAS unsigned short*)lds;
;     const GAS f16* QI = (const GAS f16*)(((GAS unsigned char*)P->ws) + WS_QI); const GAS f16* KI = (const GAS f16*)(((GAS unsigned char*)P->ws) + WS_KI); const GAS float* WI = (const GAS float*)(((GAS unsigned char*)P->ws) + WS_WI);
;     const int ntiles = (t0 + 8 + 31) >> 5, nkp = ntiles * 32;
;     const int n = lane & 31, g = lane >> 5;
;     h8 A[2][4]; float w[2][2][8];
; #pragma unroll
;     for (int mt = 0; mt < 2; ++mt) {
;         const int ql = 2 * ((n >> 2) & 1) + (n >> 4), head = 4 * ((n >> 3) & 1) + (n & 3);
;         const GAS h8* src = (const GAS h8*)(QI + (size_t)(b * SEQ + t0 + 4 * mt + ql) * 512 + head * 64 + 32 * g);
; #pragma unroll
;         for (int kk = 0; kk < 4; ++kk) A[mt][kk] = src[kk];
; #pragma unroll
;         for (int qq = 0; qq < 2; ++qq) { const GAS float* wp = WI + (size_t)(b * SEQ + t0 + 4 * mt + 2 * g + qq) * 8;
;             const f32x4 wa = *(const GAS f32x4*)wp, wb = *(const GAS f32x4*)(wp + 4);
; #pragma unroll
;             for (int h = 0; h < 4; ++h) { w[mt][qq][h] = wa[h]; w[mt][qq][4 + h] = wb[h]; } }
;     }
;     h8 B0a[4], B0b[4], B1a[4], B1b[4];
;     {   const int ta = (wave < ntiles) ? wave : 0, tb = (wave + NW < ntiles) ? wave + NW : ta;
;         const GAS h8* pa = (const GAS h8*)(KI + (size_t)(b * SEQ + ta * 32 + n) * 64 + 32 * g);
;         const GAS h8* pb = (const GAS h8*)(KI + (size_t)(b * SEQ + tb * 32 + n) * 64 + 32 * g);
; #pragma unroll
;         for (int kk = 0; kk < 4; ++kk) { B0a[kk] = pa[kk]; B0b[kk] = pb[kk]; } }
;     for (int tile = wave; tile < ntiles; tile += 4 * NW) {
; template <int MODE> __device__ __forceinline__ void indexer_phase(KP P, LAS unsigned char* lds, int G, int c, int wave, int lane) {
;     *(LAS u32x4*)(lds + 131072 + (wave * 64 + lane) * 16) = (u32x4){0u, 0u, 0u, 0u};
;     __syncthreads();
;     if (G == 256) {
;         for (int rr = 0; rr < 8; ++rr) { const int b = rr >> 2, q = rr & 3;
;             const int blk = (q == 0) ? c : (q == 1) ? 511 - c : (q == 2) ? 512 + c : 1023 - c;
;             if (8 * blk + 7 >= 256) indexer_item<MODE>(P, lds, b, 8 * blk, wave, lane); else causal_masks(P, b, 8 * blk + wave, lane); }
.LBB0_434:
	s_andn2_b64 vcc, exec, s[6:7]
	s_cbranch_vccnz .LBB0_519
	v_lshrrev_b32_e32 v0, 1, v188
	v_bfe_u32 v2, v188, 4, 1
	v_ashrrev_i32_e32 v189, 31, v188
	v_and_b32_e32 v208, 31, v188
	v_ashrrev_i32_e32 v1, 5, v188
	v_and_or_b32 v209, v0, 2, v2
	v_and_b32_e32 v2, 3, v188
	s_add_i32 s8, 0, 0x20000
	v_lshlrev_b64 v[4:5], v188, -1
	v_lshlrev_b64 v[190:191], 16, v[188:189]
	v_and_or_b32 v0, v0, 4, v2
	v_and_b32_e32 v2, 0xffffffe0, v188
	v_lshlrev_b32_e32 v210, 1, v1
	v_lshl_add_u32 v212, v1, 11, s8
	s_lshl_b32 s20, s84, 14
	v_not_b32_e32 v189, v5
	v_add_u32_e32 v196, 64, v188
	v_lshl_add_u32 v1, v1, 15, s78
	v_lshlrev_b32_e32 v5, 1, v208
	v_lshlrev_b32_e32 v0, 6, v0
	v_mov_b32_e32 v193, 0
	v_ashrrev_i32_e32 v3, 31, v2
	v_or_b32_e32 v213, 1, v210
	v_add_u32_e32 v215, 4, v210
	v_add_u32_e32 v217, 5, v210
	v_lshlrev_b32_e32 v219, 2, v188
	s_add_i32 s43, s85, 0x22000
	v_not_b32_e32 v194, v4
	v_ashrrev_i32_e32 v197, 31, v196
	v_lshlrev_b32_e32 v4, 3, v196
	v_add3_u32 v1, v1, v5, 0
	s_add_i32 s20, s20, 0
	v_mbcnt_hi_u32_b32 v229, -1, v195
	v_mov_b32_e32 v230, 0x80
	s_sub_i32 s4, 0x1ff, s2
	s_add_i32 s5, s2, 0x200
	s_sub_i32 s33, 0x3ff, s2
	v_cmp_gt_i32_e64 s[6:7], 4, v188
	v_lshlrev_b32_e32 v207, 6, v188
	s_add_i32 s42, s84, 8
	v_lshl_or_b32 v211, s84, 5, v208
	s_mov_b32 s41, 0
	v_lshl_add_u32 v214, v213, 10, s8
	v_lshl_add_u32 v216, v215, 10, s8
	v_lshl_add_u32 v218, v217, 10, s8
	v_lshl_add_u32 v220, v188, 4, s3
	v_cmp_gt_i32_e64 s[8:9], 63, v188
	v_cmp_gt_i32_e64 s[10:11], 62, v188
	v_cmp_gt_i32_e64 s[12:13], 60, v188
	v_cmp_gt_i32_e64 s[14:15], 56, v188
	v_cmp_gt_i32_e64 s[16:17], 48, v188
	v_cmp_gt_i32_e64 s[18:19], 32, v188
	v_or_b32_e32 v221, 3, v219
	v_or_b32_e32 v222, 2, v219
	v_or_b32_e32 v223, 1, v219
	v_lshlrev_b32_e32 v224, 3, v188
	v_lshlrev_b64 v[198:199], 16, v[196:197]
	v_add_u32_e32 v197, 0x10000, v1
	v_add_u32_e32 v225, s20, v205
	v_lshlrev_b32_e32 v192, 1, v0
	v_lshlrev_b64 v[200:201], 1, v[2:3]
	v_lshlrev_b32_e32 v244, 4, v188
	v_mov_b32_e32 v245, 0
	s_mov_b64 s[46:47], 0x7800000
	v_mov_b32_e32 v226, 0x47000080
	s_mov_b32 s62, 0xffff
	v_mov_b32_e32 v227, 1
	s_movk_i32 s63, 0x100
	s_movk_i32 s64, 0xff
	v_add_u32_e32 v228, s43, v4
	v_lshl_or_b32 v231, v229, 2, v230
	v_mov_b32_e32 v240, v193
	v_mov_b32_e32 v241, v193
	v_mov_b32_e32 v242, v193
	v_mov_b32_e32 v243, v193
	v_mov_b32_e32 v232, 0xffffff80
	s_mov_b32 s65, 0
	s_branch .LBB0_438

; #define GAS __attribute__((address_space(1)))
; template <int MODE> __device__ __forceinline__ void indexer_item(KP P, LAS unsigned char* lds, int b, int t0, int wave, int lane) {
;     ...
;     h8 A[2][4]; float w[2][2][8];
; #pragma unroll
;     for (int mt = 0; mt < 2; ++mt) {
;         const int ql = 2 * ((n >> 2) & 1) + (n >> 4), head = 4 * ((n >> 3) & 1) + (n & 3);
;         const GAS h8* src = (const GAS h8*)(QI + (size_t)(b * SEQ + t0 + 4 * mt + ql) * 512 + head * 64 + 32 * g);
; #pragma unroll
;         for (int kk = 0; kk < 4; ++kk) A[mt][kk] = src[kk];
; #pragma unroll
;         for (int qq = 0; qq < 2; ++qq) { const GAS float* wp = WI + (size_t)(b * SEQ + t0 + 4 * mt + 2 * g + qq) * 8;
;             const f32x4 wa = *(const GAS f32x4*)wp, wb = *(const GAS f32x4*)(wp + 4);
; #pragma unroll
;             for (int h = 0; h < 4; ++h) { w[mt][qq][h] = wa[h]; w[mt][qq][4 + h] = wb[h]; } }
;     }
;     h8 B0a[4], B0b[4], B1a[4], B1b[4];
;     {   const int ta = (wave < ntiles) ? wave : 0, tb = (wave + NW < ntiles) ? wave + NW : ta;
;         const GAS h8* pa = (const GAS h8*)(KI + (size_t)(b * SEQ + ta * 32 + n) * 64 + 32 * g);
;         const GAS h8* pb = (const GAS h8*)(KI + (size_t)(b * SEQ + tb * 32 + n) * 64 + 32 * g);
; #pragma unroll
;         for (int kk = 0; kk < 4; ++kk) { B0a[kk] = pa[kk]; B0b[kk] = pb[kk]; } }
.LBB0_448:
	s_load_dwordx2 s[48:49], s[38:39], 0xa8
	s_add_i32 s26, s40, 39
	s_lshr_b32 s22, s26, 5
	s_cmp_ge_u32 s84, s22
	s_cbranch_scc1 .LBB0_456
	s_waitcnt lgkmcnt(0)
	s_add_u32 s20, s48, 0x8a00000
	s_addc_u32 s21, s49, 0
	s_lshl_b32 s25, s66, 13
	s_add_i32 s23, s40, s25
	v_lshl_add_u64 v[0:1], s[48:49], 0, v[192:193]
	v_lshl_add_u64 v[0:1], v[0:1], 0, v[200:201]
	v_or_b32_e32 v2, s23, v209
	v_mov_b32_e32 v3, v193
	v_lshl_add_u64 v[0:1], v[0:1], 0, s[46:47]
	v_lshlrev_b64 v[2:3], 10, v[2:3]
	v_lshl_add_u64 v[2:3], v[0:1], 0, v[2:3]
	global_load_dwordx4 v[60:63], v[2:3], off
	global_load_dwordx4 v[64:67], v[2:3], off offset:16
	global_load_dwordx4 v[68:71], v[2:3], off offset:32
	global_load_dwordx4 v[72:75], v[2:3], off offset:48
	v_add_u32_e32 v2, s23, v210
	v_ashrrev_i32_e32 v3, 31, v2
	v_lshlrev_b64 v[2:3], 5, v[2:3]
	v_lshl_add_u64 v[2:3], s[20:21], 0, v[2:3]
	s_or_b32 s23, s23, 4
	global_load_dwordx4 v[76:79], v[2:3], off
	global_load_dwordx4 v[80:83], v[2:3], off offset:16
	global_load_dwordx4 v[84:87], v[2:3], off offset:32
	global_load_dwordx4 v[88:91], v[2:3], off offset:48
	v_or_b32_e32 v2, s23, v209
	v_mov_b32_e32 v3, v193
	v_lshlrev_b64 v[2:3], 10, v[2:3]
	v_lshl_add_u64 v[0:1], v[0:1], 0, v[2:3]
	global_load_dwordx4 v[92:95], v[0:1], off
	global_load_dwordx4 v[96:99], v[0:1], off offset:16
	global_load_dwordx4 v[100:103], v[0:1], off offset:32
	global_load_dwordx4 v[104:107], v[0:1], off offset:48
	v_add_u32_e32 v0, s23, v210
	v_ashrrev_i32_e32 v1, 31, v0
	v_lshlrev_b64 v[0:1], 5, v[0:1]
	s_add_i32 s23, s22, -8
	s_sub_i32 s24, s22, 24
	v_lshl_add_u64 v[0:1], s[20:21], 0, v[0:1]
	s_add_u32 s20, s48, 0x8800000
	s_addc_u32 s21, s49, 0
	s_cmp_lt_u32 s42, s22
	s_cselect_b32 s27, s42, s84
	s_lshl_b32 s27, s27, 5
	s_add_i32 s27, s27, s25
	global_load_dwordx4 v[108:111], v[0:1], off
	global_load_dwordx4 v[112:115], v[0:1], off offset:16
	global_load_dwordx4 v[116:119], v[0:1], off offset:32
	global_load_dwordx4 v[120:123], v[0:1], off offset:48
	v_mov_b32_e32 v0, s27
	v_mov_b32_e32 v1, v193
	v_lshlrev_b64 v[0:1], 7, v[0:1]
	v_lshl_add_u64 v[0:1], s[20:21], 0, v[0:1]
	v_lshl_add_u64 v[0:1], v[0:1], 0, v[244:245]
	global_load_dwordx4 v[124:127], v[0:1], off
	global_load_dwordx4 v[128:131], v[0:1], off offset:1024
	global_load_dwordx4 v[132:135], v[0:1], off offset:2048
	global_load_dwordx4 v[136:139], v[0:1], off offset:3072
	v_mov_b32_e32 v0, s25
	v_lshl_add_u32 v0, s84, 5, v0
	v_ashrrev_i32_e32 v1, 31, v0
	v_lshlrev_b64 v[0:1], 7, v[0:1]
	v_lshl_add_u64 v[0:1], s[20:21], 0, v[0:1]
	v_lshl_add_u64 v[0:1], v[0:1], 0, v[244:245]
	global_load_dwordx4 v[140:143], v[0:1], off
	global_load_dwordx4 v[144:147], v[0:1], off offset:1024
	global_load_dwordx4 v[148:151], v[0:1], off offset:2048
	global_load_dwordx4 v[152:155], v[0:1], off offset:3072
	v_mov_b32_e32 v233, s25
	v_lshl_add_u64 v[202:203], s[20:21], 0, v[244:245]
	v_add_u32_e32 v234, s40, v210
	v_add_u32_e32 v235, s40, v213
	v_add_u32_e32 v236, s40, v215
	v_add_u32_e32 v237, s40, v217
	v_mov_b32_e32 v238, v197
	v_mov_b32_e32 v239, v211
	s_mov_b32 s25, s84
	s_branch .LBB0_451

; template <int MODE> __device__ __forceinline__ void indexer_pair(LAS unsigned char* lds, const GAS f16* KI, int b, int t0, int ntiles, int tile, int n, int g,
;         const h8 (&A)[2][4], const float (&w)[2][2][8], const h8 (&BA)[4], const h8 (&BB)[4], h8 (&NA)[4], h8 (&NB)[4]) {
;     LAS unsigned short* KS = (LAS unsigned short*)lds;
;         const bool hasB = tile + NW < ntiles;
;         const int tna = (tile + 2 * NW < ntiles) ? tile + 2 * NW : tile, tnb = (tile + 3 * NW < ntiles) ? tile + 3 * NW : tna;
;         const GAS h8* pa = (const GAS h8*)(KI + (size_t)(b * SEQ + tna * 32 + n) * 64 + 32 * g);
;         const GAS h8* pb = (const GAS h8*)(KI + (size_t)(b * SEQ + tnb * 32 + n) * 64 + 32 * g);
;         #pragma unroll
;         for (int kk = 0; kk < 4; ++kk) { NA[kk] = pa[kk]; NB[kk] = pb[kk]; }
;         f32x16 cA[2], cB[2];
; #pragma unroll
;         for (int mt = 0; mt < 2; ++mt) { cA[mt] = __builtin_amdgcn_mfma_f32_32x32x16_f16(A[mt][0], BA[0], f32x16{}, 0, 0, 0); cB[mt] = __builtin_amdgcn_mfma_f32_32x32x16_f16(A[mt][0], BB[0], f32x16{}, 0, 0, 0); }
; #pragma unroll
;         for (int kk = 1; kk < 4; ++kk)
; #pragma unroll
;             for (int mt = 0; mt < 2; ++mt) { cA[mt] = __builtin_amdgcn_mfma_f32_32x32x16_f16(A[mt][kk], BA[kk], cA[mt], 0, 0, 0); cB[mt] = __builtin_amdgcn_mfma_f32_32x32x16_f16(A[mt][kk], BB[kk], cB[mt], 0, 0, 0); }
; #pragma unroll
;         for (int u = 0; u < 2; ++u) {
;             const int s = (tile + u * NW) * 32 + n;
;             if (u == 0 || hasB) {
; #pragma unroll
;                 for (int mt = 0; mt < 2; ++mt)
; #pragma unroll
;                     for (int qq = 0; qq < 2; ++qq) {
;                         float sc = 0.f;
; #pragma unroll
;                         for (int h = 0; h < 8; ++h) sc += w[mt][qq][h] * fmaxf(u ? cB[mt][8 * qq + h] : cA[mt][8 * qq + h], 0.f);
;                         const int ql = 4 * mt + 2 * g + qq;
;                         int key = (int)(sc * 4096.f + 32768.5f);
;                         key = key < 1 ? 1 : (key > 65535 ? 65535 : key);
;                         if (s > t0 + ql) key = 0;
;                         KS[ql * SEQ + s] = (unsigned short)key;
;                         __hip_atomic_fetch_add((LAS unsigned*)(lds + 131072) + ql * 256 + (key >> 8), 1u, __ATOMIC_RELAXED, __HIP_MEMORY_SCOPE_WORKGROUP);
;                     }
;             }
;         }
.LBB0_451:
	s_waitcnt vmcnt(3)
	v_mfma_f32_32x32x16_f16 v[28:43], v[60:63], v[140:143], 0
	s_add_i32 s27, s25, 16
	s_cmp_lt_u32 s27, s22
	s_cselect_b64 s[20:21], -1, 0
	s_and_b64 s[50:51], s[20:21], exec
	s_cselect_b32 s36, s27, s25
	s_add_i32 s37, s25, 24
	s_cmp_lt_u32 s37, s22
	s_waitcnt vmcnt(2)
	v_mfma_f32_32x32x16_f16 v[28:43], v[64:67], v[144:147], v[28:43]
	s_cselect_b32 s37, s37, s36
	v_lshl_add_u32 v0, s36, 5, v233
	v_ashrrev_i32_e32 v1, 31, v0
	v_lshl_add_u32 v2, s37, 5, v233
	v_lshlrev_b64 v[0:1], 7, v[0:1]
	v_ashrrev_i32_e32 v3, 31, v2
	v_lshl_add_u64 v[0:1], v[202:203], 0, v[0:1]
	s_waitcnt vmcnt(1)
	v_mfma_f32_32x32x16_f16 v[28:43], v[68:71], v[148:151], v[28:43]
	v_lshlrev_b64 v[2:3], 7, v[2:3]
	s_waitcnt vmcnt(0)
	v_lshl_add_u64 v[156:157], v[202:203], 0, v[2:3]
	global_load_dwordx4 v[184:187], v[0:1], off
	global_load_dwordx4 v[172:175], v[0:1], off offset:1024
	global_load_dwordx4 v[176:179], v[156:157], off
	global_load_dwordx4 v[168:171], v[156:157], off offset:1024
	global_load_dwordx4 v[164:167], v[0:1], off offset:2048
	global_load_dwordx4 v[160:163], v[0:1], off offset:3072
	global_load_dwordx4 v[180:183], v[156:157], off offset:2048
	s_nop 0
	global_load_dwordx4 v[156:159], v[156:157], off offset:3072
	v_cmp_le_i32_e32 vcc, v239, v234
	s_cmp_ge_i32 s25, s23
	s_waitcnt vmcnt(8)
	v_mfma_f32_32x32x16_f16 v[28:43], v[72:75], v[152:155], v[28:43]
	v_mfma_f32_32x32x16_f16 v[44:59], v[92:95], v[140:143], 0
	s_nop 10
	v_max_f32_e32 v0, v28, v28
	v_max_f32_e32 v1, v29, v29
	v_max_f32_e32 v0, 0, v0
	v_max_f32_e32 v2, v30, v30
	v_max_f32_e32 v1, 0, v1
	v_fma_f32 v0, v76, v0, 0
	v_max_f32_e32 v3, v31, v31
	v_max_f32_e32 v2, 0, v2
	v_fmac_f32_e32 v0, v77, v1
	v_max_f32_e32 v3, 0, v3
	v_fmac_f32_e32 v0, v78, v2
	v_max_f32_e32 v1, v32, v32
	v_fmac_f32_e32 v0, v79, v3
	v_max_f32_e32 v1, 0, v1
	v_fmac_f32_e32 v0, v80, v1
	v_max_f32_e32 v1, v33, v33
	v_max_f32_e32 v1, 0, v1
	v_fmac_f32_e32 v0, v81, v1
	v_max_f32_e32 v1, v34, v34
	v_max_f32_e32 v1, 0, v1
	v_fmac_f32_e32 v0, v82, v1
	v_max_f32_e32 v1, v35, v35
	v_max_f32_e32 v1, 0, v1
	v_fmac_f32_e32 v0, v83, v1
	v_fmamk_f32 v0, v0, 0x45800000, v226
	v_cvt_i32_f32_e32 v32, v0
	v_add_u32_e32 v33, 0xffff0000, v238
	v_mfma_f32_32x32x16_f16 v[44:59], v[96:99], v[144:147], v[44:59]
	v_max_f32_e32 v34, v37, v37
	v_med3_i32 v32, v32, 1, s62
	v_cndmask_b32_e32 v32, 0, v32, vcc
	ds_write_b16 v33, v32
	v_max_f32_e32 v33, v36, v36
	v_max_f32_e32 v33, 0, v33
	v_fma_f32 v33, v84, v33, 0
	v_max_f32_e32 v34, 0, v34
	v_fmac_f32_e32 v33, v85, v34
	v_max_f32_e32 v34, v38, v38
	v_max_f32_e32 v34, 0, v34
	v_fmac_f32_e32 v33, v86, v34
	v_max_f32_e32 v34, v39, v39
	v_max_f32_e32 v34, 0, v34
	v_fmac_f32_e32 v33, v87, v34
	v_max_f32_e32 v34, v40, v40
	v_mfma_f32_32x32x16_f16 v[44:59], v[100:103], v[148:151], v[44:59]
	v_max_f32_e32 v34, 0, v34
	v_fmac_f32_e32 v33, v88, v34
	v_max_f32_e32 v34, v41, v41
	v_max_f32_e32 v34, 0, v34
	v_fmac_f32_e32 v33, v89, v34
	v_max_f32_e32 v34, v42, v42
	v_max_f32_e32 v34, 0, v34
	v_fmac_f32_e32 v33, v90, v34
	v_max_f32_e32 v34, v43, v43
	v_max_f32_e32 v34, 0, v34
	v_fmac_f32_e32 v33, v91, v34
	v_mfma_f32_32x32x16_f16 v[44:59], v[104:107], v[152:155], v[44:59]
	v_fmamk_f32 v33, v33, 0x45800000, v226
	v_cvt_i32_f32_e32 v33, v33
	v_bfe_u32 v32, v32, 8, 8
	v_lshl_add_u32 v32, v32, 2, v212
	ds_add_u32 v32, v227
	v_med3_i32 v32, v33, 1, s62
	v_cmp_le_i32_e32 vcc, v239, v235
	v_add_u32_e32 v33, 0xffff4000, v238
	s_nop 3
	v_max_f32_e32 v34, v45, v45
	v_cndmask_b32_e32 v32, 0, v32, vcc
	ds_write_b16 v33, v32
	v_max_f32_e32 v33, v44, v44
	v_max_f32_e32 v33, 0, v33
	v_fma_f32 v33, v108, v33, 0
	v_max_f32_e32 v34, 0, v34
	v_fmac_f32_e32 v33, v109, v34
	v_max_f32_e32 v34, v46, v46
	v_max_f32_e32 v34, 0, v34
	v_fmac_f32_e32 v33, v110, v34
	v_max_f32_e32 v34, v47, v47
	v_max_f32_e32 v34, 0, v34
	v_fmac_f32_e32 v33, v111, v34
	v_max_f32_e32 v34, v48, v48
	v_max_f32_e32 v34, 0, v34
	v_fmac_f32_e32 v33, v112, v34
	v_max_f32_e32 v34, v49, v49
	v_max_f32_e32 v34, 0, v34
	v_fmac_f32_e32 v33, v113, v34
	v_max_f32_e32 v34, v50, v50
	v_max_f32_e32 v34, 0, v34
	v_fmac_f32_e32 v33, v114, v34
	v_max_f32_e32 v34, v51, v51
	v_max_f32_e32 v34, 0, v34
	v_fmac_f32_e32 v33, v115, v34
	v_fmamk_f32 v33, v33, 0x45800000, v226
	v_cvt_i32_f32_e32 v33, v33
	v_mfma_f32_32x32x16_f16 v[16:31], v[60:63], v[124:127], 0
	v_bfe_u32 v32, v32, 8, 8
	v_lshl_add_u32 v32, v32, 2, v214
	ds_add_u32 v32, v227
	v_med3_i32 v32, v33, 1, s62
	v_max_f32_e32 v33, v52, v52
	v_max_f32_e32 v33, 0, v33
	v_max_f32_e32 v34, v53, v53
	v_mfma_f32_32x32x16_f16 v[0:15], v[92:95], v[124:127], 0
	v_fma_f32 v33, v116, v33, 0
	v_max_f32_e32 v34, 0, v34
	v_fmac_f32_e32 v33, v117, v34
	v_max_f32_e32 v34, v54, v54
	v_max_f32_e32 v34, 0, v34
	v_fmac_f32_e32 v33, v118, v34
	v_max_f32_e32 v34, v55, v55
	v_mfma_f32_32x32x16_f16 v[16:31], v[64:67], v[128:131], v[16:31]
	v_max_f32_e32 v34, 0, v34
	v_fmac_f32_e32 v33, v119, v34
	v_max_f32_e32 v34, v56, v56
	v_max_f32_e32 v34, 0, v34
	v_fmac_f32_e32 v33, v120, v34
	v_max_f32_e32 v34, v57, v57
	v_max_f32_e32 v34, 0, v34
	v_mfma_f32_32x32x16_f16 v[0:15], v[96:99], v[128:131], v[0:15]
	v_fmac_f32_e32 v33, v121, v34
	v_max_f32_e32 v34, v58, v58
	v_max_f32_e32 v34, 0, v34
	v_fmac_f32_e32 v33, v122, v34
	v_max_f32_e32 v34, v59, v59
	v_max_f32_e32 v34, 0, v34
	v_fmac_f32_e32 v33, v123, v34
	v_mfma_f32_32x32x16_f16 v[16:31], v[68:71], v[132:135], v[16:31]
	v_fmamk_f32 v33, v33, 0x45800000, v226
	v_cmp_le_i32_e32 vcc, v239, v236
	v_cvt_i32_f32_e32 v33, v33
	s_nop 0
	v_cndmask_b32_e32 v32, 0, v32, vcc
	ds_write_b16 v238, v32
	v_bfe_u32 v32, v32, 8, 8
	v_mfma_f32_32x32x16_f16 v[0:15], v[100:103], v[132:135], v[0:15]
	v_lshl_add_u32 v32, v32, 2, v216
	ds_add_u32 v32, v227
	v_med3_i32 v32, v33, 1, s62
	v_cmp_le_i32_e32 vcc, v239, v237
	s_nop 1
	v_cndmask_b32_e32 v32, 0, v32, vcc
	v_mfma_f32_32x32x16_f16 v[16:31], v[72:75], v[136:139], v[16:31]
	ds_write_b16 v238, v32 offset:16384
	v_bfe_u32 v32, v32, 8, 8
	v_lshl_add_u32 v32, v32, 2, v218
	ds_add_u32 v32, v227
	v_mfma_f32_32x32x16_f16 v[0:15], v[104:107], v[136:139], v[0:15]
	s_cbranch_scc1 .LBB0_453
; #define LAS __attribute__((address_space(3)))
; template <int MODE> __device__ __forceinline__ void indexer_pair(LAS unsigned char* lds, const GAS f16* KI, int b, int t0, int ntiles, int tile, int n, int g,
;         const h8 (&A)[2][4], const float (&w)[2][2][8], const h8 (&BA)[4], const h8 (&BB)[4], h8 (&NA)[4], h8 (&NB)[4]) {
;     ...
; #pragma unroll
;         for (int u = 0; u < 2; ++u) {
;             const int s = (tile + u * NW) * 32 + n;
;             if (u == 0 || hasB) {
; #pragma unroll
;                 for (int mt = 0; mt < 2; ++mt)
; #pragma unroll
;                     for (int qq = 0; qq < 2; ++qq) {
;                         float sc = 0.f;
; #pragma unroll
;                         for (int h = 0; h < 8; ++h) sc += w[mt][qq][h] * fmaxf(u ? cB[mt][8 * qq + h] : cA[mt][8 * qq + h], 0.f);
;                         const int ql = 4 * mt + 2 * g + qq;
;                         int key = (int)(sc * 4096.f + 32768.5f);
;                         key = key < 1 ? 1 : (key > 65535 ? 65535 : key);
;                         if (s > t0 + ql) key = 0;
;                         KS[ql * SEQ + s] = (unsigned short)key;
;                         __hip_atomic_fetch_add((LAS unsigned*)(lds + 131072) + ql * 256 + (key >> 8), 1u, __ATOMIC_RELAXED, __HIP_MEMORY_SCOPE_WORKGROUP);
;                     }
;             }
;         }
; template <int MODE> __device__ __forceinline__ void indexer_item(KP P, LAS unsigned char* lds, int b, int t0, int wave, int lane) {
;     ...
;     for (int tile = wave; tile < ntiles; tile += 4 * NW) {
;         indexer_pair<MODE>(lds, KI, b, t0, ntiles, tile, n, g, A, w, B0a, B0b, B1a, B1b);
;         if (tile + 2 * NW < ntiles) indexer_pair<MODE>(lds, KI, b, t0, ntiles, tile + 2 * NW, n, g, A, w, B1a, B1b, B0a, B0b);
;     }
	s_nop 5
	v_max_f32_e32 v16, v16, v16
	v_max_f32_e32 v16, 0, v16
	v_max_f32_e32 v17, v17, v17
	v_fma_f32 v16, v76, v16, 0
	v_max_f32_e32 v17, 0, v17
	v_fmac_f32_e32 v16, v77, v17
	v_max_f32_e32 v17, v18, v18
	v_max_f32_e32 v17, 0, v17
	v_fmac_f32_e32 v16, v78, v17
	v_max_f32_e32 v17, v19, v19
	v_max_f32_e32 v17, 0, v17
	v_fmac_f32_e32 v16, v79, v17
	v_max_f32_e32 v17, v20, v20
	v_max_f32_e32 v17, 0, v17
	v_fmac_f32_e32 v16, v80, v17
	v_max_f32_e32 v17, v21, v21
	v_max_f32_e32 v17, 0, v17
	v_fmac_f32_e32 v16, v81, v17
	v_max_f32_e32 v17, v22, v22
	v_max_f32_e32 v17, 0, v17
	v_fmac_f32_e32 v16, v82, v17
	v_max_f32_e32 v17, v23, v23
	v_max_f32_e32 v17, 0, v17
	v_fmac_f32_e32 v16, v83, v17
	v_fmamk_f32 v16, v16, 0x45800000, v226
	v_cvt_i32_f32_e32 v16, v16
	v_add_u32_e32 v17, 0x100, v239
	v_cmp_le_i32_e32 vcc, v17, v234
	v_add_u32_e32 v18, 0xffff0200, v238
	v_med3_i32 v16, v16, 1, s62
	v_cndmask_b32_e32 v16, 0, v16, vcc
	ds_write_b16 v18, v16
	v_max_f32_e32 v18, v24, v24
	v_max_f32_e32 v18, 0, v18
	v_max_f32_e32 v19, v25, v25
	v_fma_f32 v18, v84, v18, 0
	v_max_f32_e32 v19, 0, v19
	v_fmac_f32_e32 v18, v85, v19
	v_max_f32_e32 v19, v26, v26
	v_max_f32_e32 v19, 0, v19
	v_fmac_f32_e32 v18, v86, v19
	v_max_f32_e32 v19, v27, v27
	v_max_f32_e32 v19, 0, v19
	v_fmac_f32_e32 v18, v87, v19
	v_max_f32_e32 v19, v28, v28
	v_max_f32_e32 v19, 0, v19
	v_max_f32_e32 v0, v0, v0
	v_fmac_f32_e32 v18, v88, v19
	v_max_f32_e32 v19, v29, v29
	v_max_f32_e32 v0, 0, v0
	v_max_f32_e32 v1, v1, v1
	v_max_f32_e32 v19, 0, v19
	v_fma_f32 v0, v108, v0, 0
	v_max_f32_e32 v1, 0, v1
	v_fmac_f32_e32 v18, v89, v19
	v_max_f32_e32 v19, v30, v30
	v_fmac_f32_e32 v0, v109, v1
	v_max_f32_e32 v1, v2, v2
	v_max_f32_e32 v19, 0, v19
	v_max_f32_e32 v1, 0, v1
	v_fmac_f32_e32 v18, v90, v19
	v_max_f32_e32 v19, v31, v31
	v_fmac_f32_e32 v0, v110, v1
	v_max_f32_e32 v1, v3, v3
	v_max_f32_e32 v19, 0, v19
	v_max_f32_e32 v1, 0, v1
	v_fmac_f32_e32 v18, v91, v19
	v_fmac_f32_e32 v0, v111, v1
	v_max_f32_e32 v1, v4, v4
	v_fmamk_f32 v18, v18, 0x45800000, v226
	v_max_f32_e32 v1, 0, v1
	v_cvt_i32_f32_e32 v18, v18
	v_fmac_f32_e32 v0, v112, v1
	v_max_f32_e32 v1, v5, v5
	v_max_f32_e32 v1, 0, v1
	v_bfe_u32 v16, v16, 8, 8
	v_fmac_f32_e32 v0, v113, v1
	v_max_f32_e32 v1, v6, v6
	v_lshl_add_u32 v16, v16, 2, v212
	v_max_f32_e32 v1, 0, v1
	ds_add_u32 v16, v227
	v_med3_i32 v16, v18, 1, s62
	v_cmp_le_i32_e32 vcc, v17, v235
	v_fmac_f32_e32 v0, v114, v1
	v_max_f32_e32 v1, v7, v7
	v_cndmask_b32_e32 v16, 0, v16, vcc
	v_max_f32_e32 v1, 0, v1
	v_add_u32_e32 v18, 0xffff4200, v238
	v_fmac_f32_e32 v0, v115, v1
	v_bfe_u32 v1, v16, 8, 8
	ds_write_b16 v18, v16
	v_lshl_add_u32 v1, v1, 2, v214
	ds_add_u32 v1, v227
	v_max_f32_e32 v1, v8, v8
	v_max_f32_e32 v1, 0, v1
	v_max_f32_e32 v2, v9, v9
	v_fma_f32 v1, v116, v1, 0
	v_max_f32_e32 v2, 0, v2
	v_fmac_f32_e32 v1, v117, v2
	v_max_f32_e32 v2, v10, v10
	v_max_f32_e32 v2, 0, v2
	v_fmac_f32_e32 v1, v118, v2
	v_max_f32_e32 v2, v11, v11
	v_max_f32_e32 v2, 0, v2
	v_fmac_f32_e32 v1, v119, v2
	v_max_f32_e32 v2, v12, v12
	v_max_f32_e32 v2, 0, v2
	v_fmac_f32_e32 v1, v120, v2
	v_max_f32_e32 v2, v13, v13
	v_max_f32_e32 v2, 0, v2
	v_fmac_f32_e32 v1, v121, v2
	v_max_f32_e32 v2, v14, v14
	v_fmamk_f32 v0, v0, 0x45800000, v226
	v_max_f32_e32 v2, 0, v2
	v_cvt_i32_f32_e32 v0, v0
	v_fmac_f32_e32 v1, v122, v2
	v_max_f32_e32 v2, v15, v15
	v_max_f32_e32 v2, 0, v2
	v_fmac_f32_e32 v1, v123, v2
	v_fmamk_f32 v1, v1, 0x45800000, v226
	v_med3_i32 v0, v0, 1, s62
	v_cmp_le_i32_e32 vcc, v17, v236
	v_cvt_i32_f32_e32 v1, v1
	s_nop 0
	v_cndmask_b32_e32 v0, 0, v0, vcc
	ds_write_b16 v238, v0 offset:512
	v_bfe_u32 v0, v0, 8, 8
	v_lshl_add_u32 v0, v0, 2, v216
	ds_add_u32 v0, v227
	v_med3_i32 v0, v1, 1, s62
	v_cmp_le_i32_e32 vcc, v17, v237
	s_nop 1
	v_cndmask_b32_e32 v0, 0, v0, vcc
	ds_write_b16 v238, v0 offset:16896
	v_bfe_u32 v0, v0, 8, 8
	v_lshl_add_u32 v0, v0, 2, v218
	ds_add_u32 v0, v227
.LBB0_453:
	s_andn2_b64 vcc, exec, s[20:21]
	s_add_i32 s20, s25, 32
	s_cbranch_vccnz .LBB0_450
	s_waitcnt vmcnt(7)
	v_mfma_f32_32x32x16_f16 v[42:57], v[60:63], v[184:187], 0
	s_cmp_lt_u32 s20, s22
	s_cselect_b32 s21, s20, s27
	s_add_i32 s27, s25, 40
	s_cmp_lt_u32 s27, s22
	s_nop 1
	v_lshl_add_u32 v0, s21, 5, v233
	s_cselect_b32 s21, s27, s21
	v_ashrrev_i32_e32 v1, 31, v0
	s_waitcnt vmcnt(6)
	v_mfma_f32_32x32x16_f16 v[42:57], v[64:67], v[172:175], v[42:57]
	v_lshl_add_u32 v2, s21, 5, v233
	v_lshlrev_b64 v[0:1], 7, v[0:1]
	v_ashrrev_i32_e32 v3, 31, v2
	v_lshl_add_u64 v[0:1], v[202:203], 0, v[0:1]
	v_lshlrev_b64 v[2:3], 7, v[2:3]
	v_lshl_add_u64 v[2:3], v[202:203], 0, v[2:3]
	global_load_dwordx4 v[140:143], v[0:1], off
	global_load_dwordx4 v[144:147], v[0:1], off offset:1024
	global_load_dwordx4 v[124:127], v[2:3], off
	global_load_dwordx4 v[128:131], v[2:3], off offset:1024
	global_load_dwordx4 v[148:151], v[0:1], off offset:2048
	global_load_dwordx4 v[152:155], v[0:1], off offset:3072
	global_load_dwordx4 v[132:135], v[2:3], off offset:2048
	global_load_dwordx4 v[136:139], v[2:3], off offset:3072
	s_waitcnt vmcnt(11)
	v_mfma_f32_32x32x16_f16 v[42:57], v[68:71], v[164:167], v[42:57]
	v_add_u32_e32 v58, 0xffff0400, v238
	s_cmp_ge_i32 s25, s24
	s_waitcnt vmcnt(10)
; #define LAS __attribute__((address_space(3)))
; template <int MODE> __device__ __forceinline__ void indexer_pair(LAS unsigned char* lds, const GAS f16* KI, int b, int t0, int ntiles, int tile, int n, int g,
;         const h8 (&A)[2][4], const float (&w)[2][2][8], const h8 (&BA)[4], const h8 (&BB)[4], h8 (&NA)[4], h8 (&NB)[4]) {
;     ...
;         for (int mt = 0; mt < 2; ++mt) { cA[mt] = __builtin_amdgcn_mfma_f32_32x32x16_f16(A[mt][0], BA[0], f32x16{}, 0, 0, 0); cB[mt] = __builtin_amdgcn_mfma_f32_32x32x16_f16(A[mt][0], BB[0], f32x16{}, 0, 0, 0); }
; #pragma unroll
;         for (int kk = 1; kk < 4; ++kk)
; #pragma unroll
;             for (int mt = 0; mt < 2; ++mt) { cA[mt] = __builtin_amdgcn_mfma_f32_32x32x16_f16(A[mt][kk], BA[kk], cA[mt], 0, 0, 0); cB[mt] = __builtin_amdgcn_mfma_f32_32x32x16_f16(A[mt][kk], BB[kk], cB[mt], 0, 0, 0); }
; #pragma unroll
;         for (int u = 0; u < 2; ++u) {
;             const int s = (tile + u * NW) * 32 + n;
;             if (u == 0 || hasB) {
; #pragma unroll
;                 for (int mt = 0; mt < 2; ++mt)
; #pragma unroll
;                     for (int qq = 0; qq < 2; ++qq) {
;                         float sc = 0.f;
; #pragma unroll
;                         for (int h = 0; h < 8; ++h) sc += w[mt][qq][h] * fmaxf(u ? cB[mt][8 * qq + h] : cA[mt][8 * qq + h], 0.f);
;                         const int ql = 4 * mt + 2 * g + qq;
;                         int key = (int)(sc * 4096.f + 32768.5f);
;                         key = key < 1 ? 1 : (key > 65535 ? 65535 : key);
;                         if (s > t0 + ql) key = 0;
;                         KS[ql * SEQ + s] = (unsigned short)key;
;                         __hip_atomic_fetch_add((LAS unsigned*)(lds + 131072) + ql * 256 + (key >> 8), 1u, __ATOMIC_RELAXED, __HIP_MEMORY_SCOPE_WORKGROUP);
;                     }
;             }
;         }
	v_mfma_f32_32x32x16_f16 v[42:57], v[72:75], v[160:163], v[42:57]
	v_mfma_f32_32x32x16_f16 v[16:31], v[60:63], v[176:179], 0
	s_nop 10
	v_max_f32_e32 v0, v42, v42
	v_max_f32_e32 v1, v43, v43
	v_max_f32_e32 v0, 0, v0
	v_max_f32_e32 v2, v44, v44
	v_max_f32_e32 v1, 0, v1
	v_fma_f32 v0, v76, v0, 0
	v_max_f32_e32 v3, v45, v45
	v_max_f32_e32 v2, 0, v2
	v_fmac_f32_e32 v0, v77, v1
	v_max_f32_e32 v4, v46, v46
	v_max_f32_e32 v3, 0, v3
	v_fmac_f32_e32 v0, v78, v2
	v_fmac_f32_e32 v0, v79, v3
	v_max_f32_e32 v1, 0, v4
	v_fmac_f32_e32 v0, v80, v1
	v_max_f32_e32 v1, v47, v47
	v_mfma_f32_32x32x16_f16 v[32:47], v[92:95], v[184:187], 0
	v_max_f32_e32 v1, 0, v1
	v_fmac_f32_e32 v0, v81, v1
	v_max_f32_e32 v1, v48, v48
	v_max_f32_e32 v1, 0, v1
	v_fmac_f32_e32 v0, v82, v1
	v_max_f32_e32 v1, v49, v49
	v_max_f32_e32 v1, 0, v1
	v_mfma_f32_32x32x16_f16 v[32:47], v[96:99], v[172:175], v[32:47]
	v_fmac_f32_e32 v0, v83, v1
	v_fmamk_f32 v0, v0, 0x45800000, v226
	v_cvt_i32_f32_e32 v48, v0
	v_add_u32_e32 v49, 0x200, v239
	v_cmp_le_i32_e32 vcc, v49, v234
	v_med3_i32 v48, v48, 1, s62
	v_mfma_f32_32x32x16_f16 v[32:47], v[100:103], v[164:167], v[32:47]
	v_cndmask_b32_e32 v48, 0, v48, vcc
	ds_write_b16 v58, v48
	v_bfe_u32 v48, v48, 8, 8
	v_lshl_add_u32 v48, v48, 2, v212
	ds_add_u32 v48, v227
	v_max_f32_e32 v48, v50, v50
	v_max_f32_e32 v48, 0, v48
	v_mfma_f32_32x32x16_f16 v[32:47], v[104:107], v[160:163], v[32:47]
	v_max_f32_e32 v50, v51, v51
	v_fma_f32 v48, v84, v48, 0
	v_max_f32_e32 v50, 0, v50
	v_fmac_f32_e32 v48, v85, v50
	v_max_f32_e32 v50, v52, v52
	v_max_f32_e32 v50, 0, v50
	v_fmac_f32_e32 v48, v86, v50
	v_max_f32_e32 v50, v53, v53
	v_max_f32_e32 v50, 0, v50
	v_fmac_f32_e32 v48, v87, v50
	v_max_f32_e32 v50, v54, v54
	v_max_f32_e32 v50, 0, v50
	v_max_f32_e32 v32, v32, v32
	v_fmac_f32_e32 v48, v88, v50
	v_max_f32_e32 v50, v55, v55
	v_max_f32_e32 v32, 0, v32
	v_max_f32_e32 v33, v33, v33
	v_max_f32_e32 v50, 0, v50
	v_fma_f32 v32, v108, v32, 0
	v_max_f32_e32 v33, 0, v33
	v_fmac_f32_e32 v48, v89, v50
	v_max_f32_e32 v50, v56, v56
	v_fmac_f32_e32 v32, v109, v33
	v_max_f32_e32 v33, v34, v34
	v_max_f32_e32 v50, 0, v50
	v_max_f32_e32 v33, 0, v33
	v_fmac_f32_e32 v48, v90, v50
	v_max_f32_e32 v50, v57, v57
	v_fmac_f32_e32 v32, v110, v33
	v_max_f32_e32 v33, v35, v35
	v_max_f32_e32 v50, 0, v50
	v_max_f32_e32 v33, 0, v33
	v_fmac_f32_e32 v48, v91, v50
	v_fmac_f32_e32 v32, v111, v33
	v_max_f32_e32 v33, v36, v36
	v_fmamk_f32 v48, v48, 0x45800000, v226
	v_max_f32_e32 v33, 0, v33
	v_cvt_i32_f32_e32 v48, v48
	v_fmac_f32_e32 v32, v112, v33
	v_max_f32_e32 v33, v37, v37
	v_max_f32_e32 v33, 0, v33
	v_fmac_f32_e32 v32, v113, v33
	v_max_f32_e32 v33, v38, v38
	v_max_f32_e32 v33, 0, v33
	v_med3_i32 v48, v48, 1, s62
	v_cmp_le_i32_e32 vcc, v49, v235
	v_fmac_f32_e32 v32, v114, v33
	v_max_f32_e32 v33, v39, v39
	v_mfma_f32_32x32x16_f16 v[0:15], v[92:95], v[176:179], 0
	v_cndmask_b32_e32 v48, 0, v48, vcc
	v_max_f32_e32 v33, 0, v33
	v_add_u32_e32 v50, 0xffff4400, v238
	v_fmac_f32_e32 v32, v115, v33
	v_bfe_u32 v33, v48, 8, 8
	ds_write_b16 v50, v48
	v_lshl_add_u32 v33, v33, 2, v214
	ds_add_u32 v33, v227
	v_max_f32_e32 v33, v40, v40
	v_max_f32_e32 v33, 0, v33
	v_max_f32_e32 v34, v41, v41
	v_fma_f32 v33, v116, v33, 0
	v_max_f32_e32 v34, 0, v34
	v_fmac_f32_e32 v33, v117, v34
	v_max_f32_e32 v34, v42, v42
	v_max_f32_e32 v34, 0, v34
	v_mfma_f32_32x32x16_f16 v[16:31], v[64:67], v[168:171], v[16:31]
	v_fmac_f32_e32 v33, v118, v34
	v_max_f32_e32 v34, v43, v43
	v_max_f32_e32 v34, 0, v34
	v_fmac_f32_e32 v33, v119, v34
	v_max_f32_e32 v34, v44, v44
	v_max_f32_e32 v34, 0, v34
	v_fmac_f32_e32 v33, v120, v34
	v_mfma_f32_32x32x16_f16 v[0:15], v[96:99], v[168:171], v[0:15]
	v_max_f32_e32 v34, v45, v45
	v_max_f32_e32 v34, 0, v34
	v_fmac_f32_e32 v33, v121, v34
	v_max_f32_e32 v34, v46, v46
	v_fmamk_f32 v32, v32, 0x45800000, v226
	v_max_f32_e32 v34, 0, v34
	v_cvt_i32_f32_e32 v32, v32
	s_waitcnt vmcnt(9)
	v_mfma_f32_32x32x16_f16 v[16:31], v[68:71], v[180:183], v[16:31]
	v_fmac_f32_e32 v33, v122, v34
	v_max_f32_e32 v34, v47, v47
	v_max_f32_e32 v34, 0, v34
	v_fmac_f32_e32 v33, v123, v34
	v_fmamk_f32 v33, v33, 0x45800000, v226
	v_med3_i32 v32, v32, 1, s62
	v_cmp_le_i32_e32 vcc, v49, v236
	v_mfma_f32_32x32x16_f16 v[0:15], v[100:103], v[180:183], v[0:15]
	v_cvt_i32_f32_e32 v33, v33
	v_cndmask_b32_e32 v32, 0, v32, vcc
	ds_write_b16 v238, v32 offset:1024
	v_bfe_u32 v32, v32, 8, 8
	v_lshl_add_u32 v32, v32, 2, v216
	ds_add_u32 v32, v227
	v_med3_i32 v32, v33, 1, s62
	s_waitcnt vmcnt(8)
	v_mfma_f32_32x32x16_f16 v[16:31], v[72:75], v[156:159], v[16:31]
	v_cmp_le_i32_e32 vcc, v49, v237
	s_nop 1
	v_cndmask_b32_e32 v32, 0, v32, vcc
	ds_write_b16 v238, v32 offset:17408
	v_bfe_u32 v32, v32, 8, 8
	v_lshl_add_u32 v32, v32, 2, v218
	v_mfma_f32_32x32x16_f16 v[0:15], v[104:107], v[156:159], v[0:15]
	ds_add_u32 v32, v227
	s_cbranch_scc1 .LBB0_450
; #define LAS __attribute__((address_space(3)))
; template <int MODE> __device__ __forceinline__ void indexer_pair(LAS unsigned char* lds, const GAS f16* KI, int b, int t0, int ntiles, int tile, int n, int g,
;         const h8 (&A)[2][4], const float (&w)[2][2][8], const h8 (&BA)[4], const h8 (&BB)[4], h8 (&NA)[4], h8 (&NB)[4]) {
;     ...
; #pragma unroll
;         for (int u = 0; u < 2; ++u) {
;             const int s = (tile + u * NW) * 32 + n;
;             if (u == 0 || hasB) {
; #pragma unroll
;                 for (int mt = 0; mt < 2; ++mt)
; #pragma unroll
;                     for (int qq = 0; qq < 2; ++qq) {
;                         float sc = 0.f;
; #pragma unroll
;                         for (int h = 0; h < 8; ++h) sc += w[mt][qq][h] * fmaxf(u ? cB[mt][8 * qq + h] : cA[mt][8 * qq + h], 0.f);
;                         const int ql = 4 * mt + 2 * g + qq;
;                         int key = (int)(sc * 4096.f + 32768.5f);
;                         key = key < 1 ? 1 : (key > 65535 ? 65535 : key);
;                         if (s > t0 + ql) key = 0;
;                         KS[ql * SEQ + s] = (unsigned short)key;
;                         __hip_atomic_fetch_add((LAS unsigned*)(lds + 131072) + ql * 256 + (key >> 8), 1u, __ATOMIC_RELAXED, __HIP_MEMORY_SCOPE_WORKGROUP);
;                     }
;             }
;         }
	s_nop 1
	v_max_f32_e32 v16, v16, v16
	v_max_f32_e32 v16, 0, v16
	v_max_f32_e32 v17, v17, v17
	v_fma_f32 v16, v76, v16, 0
	v_max_f32_e32 v17, 0, v17
	v_fmac_f32_e32 v16, v77, v17
	v_max_f32_e32 v17, v18, v18
	v_max_f32_e32 v17, 0, v17
	v_fmac_f32_e32 v16, v78, v17
	v_max_f32_e32 v17, v19, v19
	v_max_f32_e32 v17, 0, v17
	v_fmac_f32_e32 v16, v79, v17
	v_max_f32_e32 v17, v20, v20
	v_max_f32_e32 v17, 0, v17
	v_fmac_f32_e32 v16, v80, v17
	v_max_f32_e32 v17, v21, v21
	v_max_f32_e32 v17, 0, v17
	v_fmac_f32_e32 v16, v81, v17
	v_max_f32_e32 v17, v22, v22
	v_max_f32_e32 v17, 0, v17
	v_fmac_f32_e32 v16, v82, v17
	v_max_f32_e32 v17, v23, v23
	v_max_f32_e32 v17, 0, v17
	v_fmac_f32_e32 v16, v83, v17
	v_fmamk_f32 v16, v16, 0x45800000, v226
	v_cvt_i32_f32_e32 v16, v16
	v_add_u32_e32 v17, 0x300, v239
	v_cmp_le_i32_e32 vcc, v17, v234
	v_add_u32_e32 v18, 0xffff0600, v238
	v_med3_i32 v16, v16, 1, s62
	v_cndmask_b32_e32 v16, 0, v16, vcc
	ds_write_b16 v18, v16
	v_max_f32_e32 v18, v24, v24
	v_max_f32_e32 v18, 0, v18
	v_max_f32_e32 v19, v25, v25
	v_fma_f32 v18, v84, v18, 0
	v_max_f32_e32 v19, 0, v19
	v_fmac_f32_e32 v18, v85, v19
	v_max_f32_e32 v19, v26, v26
	v_max_f32_e32 v19, 0, v19
	v_fmac_f32_e32 v18, v86, v19
	v_max_f32_e32 v19, v27, v27
	v_max_f32_e32 v19, 0, v19
	v_fmac_f32_e32 v18, v87, v19
	v_max_f32_e32 v19, v28, v28
	v_max_f32_e32 v19, 0, v19
	v_max_f32_e32 v0, v0, v0
	v_fmac_f32_e32 v18, v88, v19
	v_max_f32_e32 v19, v29, v29
	v_max_f32_e32 v0, 0, v0
	v_max_f32_e32 v1, v1, v1
	v_max_f32_e32 v19, 0, v19
	v_fma_f32 v0, v108, v0, 0
	v_max_f32_e32 v1, 0, v1
	v_fmac_f32_e32 v18, v89, v19
	v_max_f32_e32 v19, v30, v30
	v_fmac_f32_e32 v0, v109, v1
	v_max_f32_e32 v1, v2, v2
	v_max_f32_e32 v19, 0, v19
	v_max_f32_e32 v1, 0, v1
	v_fmac_f32_e32 v18, v90, v19
	v_max_f32_e32 v19, v31, v31
	v_fmac_f32_e32 v0, v110, v1
	v_max_f32_e32 v1, v3, v3
	v_max_f32_e32 v19, 0, v19
	v_max_f32_e32 v1, 0, v1
	v_fmac_f32_e32 v18, v91, v19
	v_fmac_f32_e32 v0, v111, v1
	v_max_f32_e32 v1, v4, v4
	v_fmamk_f32 v18, v18, 0x45800000, v226
	v_max_f32_e32 v1, 0, v1
	v_cvt_i32_f32_e32 v18, v18
	v_fmac_f32_e32 v0, v112, v1
	v_max_f32_e32 v1, v5, v5
	v_max_f32_e32 v1, 0, v1
	v_bfe_u32 v16, v16, 8, 8
	v_fmac_f32_e32 v0, v113, v1
	v_max_f32_e32 v1, v6, v6
	v_lshl_add_u32 v16, v16, 2, v212
	v_max_f32_e32 v1, 0, v1
	ds_add_u32 v16, v227
	v_med3_i32 v16, v18, 1, s62
	v_cmp_le_i32_e32 vcc, v17, v235
	v_fmac_f32_e32 v0, v114, v1
	v_max_f32_e32 v1, v7, v7
	v_cndmask_b32_e32 v16, 0, v16, vcc
	v_max_f32_e32 v1, 0, v1
	v_add_u32_e32 v18, 0xffff4600, v238
	v_fmac_f32_e32 v0, v115, v1
	v_bfe_u32 v1, v16, 8, 8
	ds_write_b16 v18, v16
	v_lshl_add_u32 v1, v1, 2, v214
	ds_add_u32 v1, v227
	v_max_f32_e32 v1, v8, v8
	v_max_f32_e32 v1, 0, v1
	v_max_f32_e32 v2, v9, v9
	v_fma_f32 v1, v116, v1, 0
	v_max_f32_e32 v2, 0, v2
	v_fmac_f32_e32 v1, v117, v2
	v_max_f32_e32 v2, v10, v10
	v_max_f32_e32 v2, 0, v2
	v_fmac_f32_e32 v1, v118, v2
	v_max_f32_e32 v2, v11, v11
	v_max_f32_e32 v2, 0, v2
	v_fmac_f32_e32 v1, v119, v2
	v_max_f32_e32 v2, v12, v12
	v_max_f32_e32 v2, 0, v2
	v_fmac_f32_e32 v1, v120, v2
	v_max_f32_e32 v2, v13, v13
	v_max_f32_e32 v2, 0, v2
	v_fmac_f32_e32 v1, v121, v2
	v_max_f32_e32 v2, v14, v14
	v_fmamk_f32 v0, v0, 0x45800000, v226
	v_max_f32_e32 v2, 0, v2
	v_cvt_i32_f32_e32 v0, v0
	v_fmac_f32_e32 v1, v122, v2
	v_max_f32_e32 v2, v15, v15
	v_max_f32_e32 v2, 0, v2
	v_fmac_f32_e32 v1, v123, v2
	v_fmamk_f32 v1, v1, 0x45800000, v226
	v_med3_i32 v0, v0, 1, s62
	v_cmp_le_i32_e32 vcc, v17, v236
	v_cvt_i32_f32_e32 v1, v1
	s_nop 0
	v_cndmask_b32_e32 v0, 0, v0, vcc
	ds_write_b16 v238, v0 offset:1536
	v_bfe_u32 v0, v0, 8, 8
	v_lshl_add_u32 v0, v0, 2, v216
	ds_add_u32 v0, v227
	v_med3_i32 v0, v1, 1, s62
	v_cmp_le_i32_e32 vcc, v17, v237
	s_nop 1
	v_cndmask_b32_e32 v0, 0, v0, vcc
	ds_write_b16 v238, v0 offset:17920
	v_bfe_u32 v0, v0, 8, 8
	v_lshl_add_u32 v0, v0, 2, v218
	ds_add_u32 v0, v227
	s_branch .LBB0_450
